# GEMM K-loops: all s_setprio toggles removed (both wave halves run at priority 0)
# speedup vs baseline: 1.0046x; 1.0016x over previous
; #define PG8_STAGE(bufoff, gbase, voff) do { _Pragma("unroll") for (int _i = 0; _i < 2; ++_i) \
;         __builtin_amdgcn_global_load_lds((const unsigned*)((const char*)(gbase) + (voff)[_i]), (PG8_LAS unsigned*)(lds + (bufoff) + ldsw + _i * 8192), 16, 0, 0); } while (0)
; #define PG8_LDA(dst, b, h) do { _Pragma("unroll") for (int m = 0; m < 4; ++m) _Pragma("unroll") for (int k = 0; k < 2; ++k) dst[m][k] = *(const PG8_LAS bf16x8*)(lds + PG8_SA(b, h) + aoff + m * 2048 + k * 1024); } while (0)
; #define PG8_LDB(dst, b, h) do { _Pragma("unroll") for (int n = 0; n < 2; ++n) _Pragma("unroll") for (int k = 0; k < 2; ++k) dst[n][k] = *(const PG8_LAS bf16x8*)(lds + PG8_SB(b, h) + boff + n * 2048 + k * 1024); } while (0)
; #define PG8_MMA(ai, bj, At, Bt) do { __builtin_amdgcn_s_setprio(1); _Pragma("unroll") for (int m = 0; m < 4; ++m) _Pragma("unroll") for (int n = 0; n < 2; ++n) _Pragma("unroll") for (int k = 0; k < 2; ++k) \
;         acc[ai][bj][m][n] = __builtin_amdgcn_mfma_f32_16x16x32_bf16(Bt[n][k], At[m][k], acc[ai][bj][m][n], 0, 0, 0); __builtin_amdgcn_s_setprio(0); } while (0)
; #define PG8_WAIT_V(n) asm volatile("s_waitcnt vmcnt(" #n ")" ::: "memory")
; #define PG8_WAIT_L(n) asm volatile("s_waitcnt lgkmcnt(" #n ")" ::: "memory")
; #define PG8_BAR __builtin_amdgcn_s_barrier()
; #define PG8_SCHED __builtin_amdgcn_sched_barrier(0)
; template <class Epi, class Sched, bool ALIGN_EPI = false, bool SP2 = false>
; __device__ __forceinline__ void gemm_phase(PG8_LAS unsigned char* lds, const Gemm g, const Sched& S, const Epi& E, const int tid_) {
;     ...
;     f32x4 acc[2][2][4][2];
; #pragma unroll
;     for (int a = 0; a < 2; ++a)
; #pragma unroll
;         for (int b = 0; b < 2; ++b)
; #pragma unroll
;             for (int m = 0; m < 4; ++m)
; #pragma unroll
;                 for (int n = 0; n < 2; ++n) acc[a][b][m][n] = (f32x4){0.f, 0.f, 0.f, 0.f};
;     ...
;             PG8_LDB(B0, 0, 0); PG8_LDB(B1, 0, 1); PG8_SCHED; PG8_LDA(At, 0, 0); PG8_STAGE(PG8_SA(1, 1), a1 + hstep, voffA);
;             PG8_WAIT_V(8); PG8_WAIT_L(0); PG8_BAR; PG8_MMA(0, 0, At, B0); PG8_MMA(0, 1, At, B1); PG8_BAR; PG8_SCHED;
;             PG8_LDA(At, 0, 1); PG8_STAGE(PG8_SB(0, 0), b2, voffB); PG8_STAGE(PG8_SB(0, 1), b2 + hstepB, voffB); PG8_STAGE(PG8_SA(0, 0), a2, voffA);
;             PG8_WAIT_V(8); PG8_WAIT_L(0); PG8_BAR; PG8_MMA(1, 0, At, B0); PG8_MMA(1, 1, At, B1); PG8_BAR; PG8_SCHED;
.Lpeel1_w1:
	s_waitcnt lgkmcnt(0)
	s_barrier
	s_waitcnt lgkmcnt(0)
	v_mfma_f32_16x16x32_bf16 v[128:131], v[132:135], v[188:191], 0
	v_mfma_f32_16x16x32_bf16 v[120:123], v[150:153], v[188:191], 0
	v_mfma_f32_16x16x32_bf16 v[112:115], v[132:135], v[196:199], 0
	v_mfma_f32_16x16x32_bf16 v[104:107], v[150:153], v[196:199], 0
	v_mfma_f32_16x16x32_bf16 v[96:99], v[132:135], v[204:207], 0
	v_mfma_f32_16x16x32_bf16 v[88:91], v[150:153], v[204:207], 0
	v_mfma_f32_16x16x32_bf16 v[80:83], v[132:135], v[212:215], 0
	v_mfma_f32_16x16x32_bf16 v[72:75], v[150:153], v[212:215], 0
	v_mfma_f32_16x16x32_bf16 v[128:131], v[146:149], v[192:195], v[128:131]
	v_mfma_f32_16x16x32_bf16 v[120:123], v[154:157], v[192:195], v[120:123]
	v_mfma_f32_16x16x32_bf16 v[112:115], v[146:149], v[200:203], v[112:115]
	v_mfma_f32_16x16x32_bf16 v[104:107], v[154:157], v[200:203], v[104:107]
	v_mfma_f32_16x16x32_bf16 v[96:99], v[146:149], v[208:211], v[96:99]
	v_mfma_f32_16x16x32_bf16 v[88:91], v[154:157], v[208:211], v[88:91]
	v_mfma_f32_16x16x32_bf16 v[80:83], v[146:149], v[216:219], v[80:83]
	v_mfma_f32_16x16x32_bf16 v[72:75], v[154:157], v[216:219], v[72:75]
	v_mfma_f32_16x16x32_bf16 v[124:127], v[158:161], v[188:191], 0
	v_mfma_f32_16x16x32_bf16 v[116:119], v[170:173], v[188:191], 0
	v_mfma_f32_16x16x32_bf16 v[108:111], v[158:161], v[196:199], 0
	v_mfma_f32_16x16x32_bf16 v[100:103], v[170:173], v[196:199], 0
	v_mfma_f32_16x16x32_bf16 v[92:95], v[158:161], v[204:207], 0
	v_mfma_f32_16x16x32_bf16 v[84:87], v[170:173], v[204:207], 0
	v_mfma_f32_16x16x32_bf16 v[76:79], v[158:161], v[212:215], 0
	v_mfma_f32_16x16x32_bf16 v[68:71], v[170:173], v[212:215], 0
	v_mfma_f32_16x16x32_bf16 v[124:127], v[166:169], v[192:195], v[124:127]
	v_mfma_f32_16x16x32_bf16 v[116:119], v[174:177], v[192:195], v[116:119]
	v_mfma_f32_16x16x32_bf16 v[108:111], v[166:169], v[200:203], v[108:111]
	v_mfma_f32_16x16x32_bf16 v[100:103], v[174:177], v[200:203], v[100:103]
	v_mfma_f32_16x16x32_bf16 v[92:95], v[166:169], v[208:211], v[92:95]
	v_mfma_f32_16x16x32_bf16 v[84:87], v[174:177], v[208:211], v[84:87]
	v_mfma_f32_16x16x32_bf16 v[76:79], v[166:169], v[216:219], v[76:79]
	v_mfma_f32_16x16x32_bf16 v[68:71], v[174:177], v[216:219], v[68:71]
	s_barrier
	s_mov_b32 m0, s35
	v_lshl_add_u64 v[178:179], s[26:27], 0, v[2:3]
	s_add_u32 s58, s26, 0x40000
	ds_read_b128 v[188:191], v165 offset:16384
	ds_read_b128 v[192:195], v165 offset:17408
	ds_read_b128 v[196:199], v165 offset:18432
	ds_read_b128 v[200:203], v165 offset:19456
	ds_read_b128 v[204:207], v165 offset:20480
	ds_read_b128 v[208:211], v165 offset:21504
	ds_read_b128 v[212:215], v165 offset:22528
	ds_read_b128 v[216:219], v165 offset:23552
	global_load_lds_dwordx4 v[178:179], off
	v_lshl_add_u64 v[220:221], s[26:27], 0, v[0:1]
	s_mov_b32 m0, s36
	s_addc_u32 s59, s27, 0
	global_load_lds_dwordx4 v[220:221], off
	v_lshl_add_u64 v[222:223], s[58:59], 0, v[2:3]
	s_mov_b32 m0, s38
	v_lshl_add_u64 v[224:225], s[28:29], 0, v[136:137]
	global_load_lds_dwordx4 v[222:223], off
	v_lshl_add_u64 v[222:223], s[58:59], 0, v[0:1]
	s_mov_b32 m0, s39
	s_nop 0
	global_load_lds_dwordx4 v[222:223], off
	v_lshl_add_u64 v[222:223], s[28:29], 0, v[138:139]
	s_mov_b32 m0, s40
	s_nop 0
	global_load_lds_dwordx4 v[222:223], off
	s_mov_b32 m0, s41
	s_nop 0
	global_load_lds_dwordx4 v[224:225], off
	s_cmp_lg_u32 s53, 1
	s_cbranch_scc1 .Lpeel1_w2
	s_waitcnt vmcnt(8)
.Lpeel1_w2:
	s_waitcnt lgkmcnt(0)
	s_barrier
	s_waitcnt lgkmcnt(0)
	v_mfma_f32_16x16x32_bf16 v[64:67], v[132:135], v[188:191], 0
	v_mfma_f32_16x16x32_bf16 v[56:59], v[150:153], v[188:191], 0
	v_mfma_f32_16x16x32_bf16 v[48:51], v[132:135], v[196:199], 0
	v_mfma_f32_16x16x32_bf16 v[40:43], v[150:153], v[196:199], 0
	v_mfma_f32_16x16x32_bf16 v[32:35], v[132:135], v[204:207], 0
	v_mfma_f32_16x16x32_bf16 v[24:27], v[150:153], v[204:207], 0
	v_mfma_f32_16x16x32_bf16 v[16:19], v[132:135], v[212:215], 0
	v_mfma_f32_16x16x32_bf16 v[8:11], v[150:153], v[212:215], 0
	v_mfma_f32_16x16x32_bf16 v[64:67], v[146:149], v[192:195], v[64:67]
	v_mfma_f32_16x16x32_bf16 v[56:59], v[154:157], v[192:195], v[56:59]
	v_mfma_f32_16x16x32_bf16 v[48:51], v[146:149], v[200:203], v[48:51]
	v_mfma_f32_16x16x32_bf16 v[40:43], v[154:157], v[200:203], v[40:43]
	v_mfma_f32_16x16x32_bf16 v[32:35], v[146:149], v[208:211], v[32:35]
	v_mfma_f32_16x16x32_bf16 v[24:27], v[154:157], v[208:211], v[24:27]
	v_mfma_f32_16x16x32_bf16 v[16:19], v[146:149], v[216:219], v[16:19]
	v_mfma_f32_16x16x32_bf16 v[8:11], v[154:157], v[216:219], v[8:11]
	v_mfma_f32_16x16x32_bf16 v[60:63], v[158:161], v[188:191], 0
	v_mfma_f32_16x16x32_bf16 v[52:55], v[170:173], v[188:191], 0
	v_mfma_f32_16x16x32_bf16 v[44:47], v[158:161], v[196:199], 0
	v_mfma_f32_16x16x32_bf16 v[36:39], v[170:173], v[196:199], 0
	v_mfma_f32_16x16x32_bf16 v[28:31], v[158:161], v[204:207], 0
	v_mfma_f32_16x16x32_bf16 v[20:23], v[170:173], v[204:207], 0
	v_mfma_f32_16x16x32_bf16 v[12:15], v[158:161], v[212:215], 0
	v_mfma_f32_16x16x32_bf16 v[4:7], v[170:173], v[212:215], 0
	v_mfma_f32_16x16x32_bf16 v[60:63], v[166:169], v[192:195], v[60:63]
	v_mfma_f32_16x16x32_bf16 v[52:55], v[174:177], v[192:195], v[52:55]
	v_mfma_f32_16x16x32_bf16 v[44:47], v[166:169], v[200:203], v[44:47]
	v_mfma_f32_16x16x32_bf16 v[36:39], v[174:177], v[200:203], v[36:39]
	v_mfma_f32_16x16x32_bf16 v[28:31], v[166:169], v[208:211], v[28:31]
	v_mfma_f32_16x16x32_bf16 v[20:23], v[174:177], v[208:211], v[20:23]
	v_mfma_f32_16x16x32_bf16 v[12:15], v[166:169], v[216:219], v[12:15]
	v_mfma_f32_16x16x32_bf16 v[4:7], v[174:177], v[216:219], v[4:7]
	s_barrier
; #define PG8_STAGE(bufoff, gbase, voff) do { _Pragma("unroll") for (int _i = 0; _i < 2; ++_i) \
;         __builtin_amdgcn_global_load_lds((const unsigned*)((const char*)(gbase) + (voff)[_i]), (PG8_LAS unsigned*)(lds + (bufoff) + ldsw + _i * 8192), 16, 0, 0); } while (0)
; #define PG8_LDA(dst, b, h) do { _Pragma("unroll") for (int m = 0; m < 4; ++m) _Pragma("unroll") for (int k = 0; k < 2; ++k) dst[m][k] = *(const PG8_LAS bf16x8*)(lds + PG8_SA(b, h) + aoff + m * 2048 + k * 1024); } while (0)
; #define PG8_LDB(dst, b, h) do { _Pragma("unroll") for (int n = 0; n < 2; ++n) _Pragma("unroll") for (int k = 0; k < 2; ++k) dst[n][k] = *(const PG8_LAS bf16x8*)(lds + PG8_SB(b, h) + boff + n * 2048 + k * 1024); } while (0)
; #define PG8_MMA(ai, bj, At, Bt) do { __builtin_amdgcn_s_setprio(1); _Pragma("unroll") for (int m = 0; m < 4; ++m) _Pragma("unroll") for (int n = 0; n < 2; ++n) _Pragma("unroll") for (int k = 0; k < 2; ++k) \
;         acc[ai][bj][m][n] = __builtin_amdgcn_mfma_f32_16x16x32_bf16(Bt[n][k], At[m][k], acc[ai][bj][m][n], 0, 0, 0); __builtin_amdgcn_s_setprio(0); } while (0)
; #define PG8_WAIT_V(n) asm volatile("s_waitcnt vmcnt(" #n ")" ::: "memory")
; #define PG8_WAIT_L(n) asm volatile("s_waitcnt lgkmcnt(" #n ")" ::: "memory")
; #define PG8_BAR __builtin_amdgcn_s_barrier()
; #define PG8_SCHED __builtin_amdgcn_sched_barrier(0)
; template <class Epi, class Sched, bool ALIGN_EPI = false, bool SP2 = false>
; __device__ __forceinline__ void gemm_phase(PG8_LAS unsigned char* lds, const Gemm g, const Sched& S, const Epi& E, const int tid_) {
;     ...
;             PG8_LDB(B0, 1, 0); PG8_LDB(B1, 1, 1); PG8_SCHED; PG8_LDA(At, 1, 0); PG8_STAGE(PG8_SA(0, 1), a2 + hstep, voffA);
;             PG8_WAIT_V(8); PG8_WAIT_L(0); PG8_BAR; PG8_MMA(0, 0, At, B0); PG8_MMA(0, 1, At, B1); PG8_BAR; PG8_SCHED;
;             PG8_LDA(At, 1, 1); PG8_STAGE(PG8_SB(1, 0), b3, voffB); PG8_STAGE(PG8_SB(1, 1), b3 + hstepB, voffB); PG8_STAGE(PG8_SA(1, 0), a3, voffA);
;             PG8_WAIT_V(8); PG8_WAIT_L(0); PG8_BAR; PG8_MMA(1, 0, At, B0); PG8_MMA(1, 1, At, B1); PG8_BAR; PG8_SCHED;
	v_add_u32_e32 v154, s44, v163
	v_add_u32_e32 v174, s49, v163
	ds_read_b128 v[132:135], v154
	ds_read_b128 v[146:149], v154 offset:1024
	ds_read_b128 v[150:153], v154 offset:2048
	ds_read_b128 v[154:157], v154 offset:3072
	ds_read_b128 v[158:161], v174
	ds_read_b128 v[166:169], v174 offset:1024
	ds_read_b128 v[170:173], v174 offset:2048
	ds_read_b128 v[174:177], v174 offset:3072
	s_add_u32 s28, s28, 0x40000
	s_addc_u32 s29, s29, 0
	s_mov_b32 m0, s42
	v_lshl_add_u64 v[226:227], s[28:29], 0, v[138:139]
	ds_read_b128 v[188:191], v165 offset:32768
	ds_read_b128 v[192:195], v165 offset:33792
	ds_read_b128 v[196:199], v165 offset:34816
	ds_read_b128 v[200:203], v165 offset:35840
	ds_read_b128 v[204:207], v165 offset:36864
	ds_read_b128 v[208:211], v165 offset:37888
	ds_read_b128 v[212:215], v165 offset:38912
	ds_read_b128 v[216:219], v165 offset:39936
	global_load_lds_dwordx4 v[226:227], off
	v_lshl_add_u64 v[226:227], s[28:29], 0, v[136:137]
	s_mov_b32 m0, s43
	s_nop 0
	global_load_lds_dwordx4 v[226:227], off
	s_waitcnt vmcnt(8)
	s_waitcnt lgkmcnt(0)
	s_barrier
	s_waitcnt lgkmcnt(0)
	v_mfma_f32_16x16x32_bf16 v[128:131], v[132:135], v[188:191], v[128:131]
	v_mfma_f32_16x16x32_bf16 v[120:123], v[150:153], v[188:191], v[120:123]
	v_mfma_f32_16x16x32_bf16 v[112:115], v[132:135], v[196:199], v[112:115]
	v_mfma_f32_16x16x32_bf16 v[104:107], v[150:153], v[196:199], v[104:107]
	v_mfma_f32_16x16x32_bf16 v[96:99], v[132:135], v[204:207], v[96:99]
	v_mfma_f32_16x16x32_bf16 v[88:91], v[150:153], v[204:207], v[88:91]
	v_mfma_f32_16x16x32_bf16 v[80:83], v[132:135], v[212:215], v[80:83]
	v_mfma_f32_16x16x32_bf16 v[72:75], v[150:153], v[212:215], v[72:75]
	v_mfma_f32_16x16x32_bf16 v[128:131], v[146:149], v[192:195], v[128:131]
	v_mfma_f32_16x16x32_bf16 v[120:123], v[154:157], v[192:195], v[120:123]
	v_mfma_f32_16x16x32_bf16 v[112:115], v[146:149], v[200:203], v[112:115]
	v_mfma_f32_16x16x32_bf16 v[104:107], v[154:157], v[200:203], v[104:107]
	v_mfma_f32_16x16x32_bf16 v[96:99], v[146:149], v[208:211], v[96:99]
	v_mfma_f32_16x16x32_bf16 v[88:91], v[154:157], v[208:211], v[88:91]
	v_mfma_f32_16x16x32_bf16 v[80:83], v[146:149], v[216:219], v[80:83]
	v_mfma_f32_16x16x32_bf16 v[72:75], v[154:157], v[216:219], v[72:75]
	v_mfma_f32_16x16x32_bf16 v[124:127], v[158:161], v[188:191], v[124:127]
	v_mfma_f32_16x16x32_bf16 v[116:119], v[170:173], v[188:191], v[116:119]
	v_mfma_f32_16x16x32_bf16 v[108:111], v[158:161], v[196:199], v[108:111]
	v_mfma_f32_16x16x32_bf16 v[100:103], v[170:173], v[196:199], v[100:103]
	v_mfma_f32_16x16x32_bf16 v[92:95], v[158:161], v[204:207], v[92:95]
	v_mfma_f32_16x16x32_bf16 v[84:87], v[170:173], v[204:207], v[84:87]
	v_mfma_f32_16x16x32_bf16 v[76:79], v[158:161], v[212:215], v[76:79]
	v_mfma_f32_16x16x32_bf16 v[68:71], v[170:173], v[212:215], v[68:71]
	v_mfma_f32_16x16x32_bf16 v[124:127], v[166:169], v[192:195], v[124:127]
	v_mfma_f32_16x16x32_bf16 v[116:119], v[174:177], v[192:195], v[116:119]
	v_mfma_f32_16x16x32_bf16 v[108:111], v[166:169], v[200:203], v[108:111]
	v_mfma_f32_16x16x32_bf16 v[100:103], v[174:177], v[200:203], v[100:103]
	v_mfma_f32_16x16x32_bf16 v[92:95], v[166:169], v[208:211], v[92:95]
	v_mfma_f32_16x16x32_bf16 v[84:87], v[174:177], v[208:211], v[84:87]
	v_mfma_f32_16x16x32_bf16 v[76:79], v[166:169], v[216:219], v[76:79]
	v_mfma_f32_16x16x32_bf16 v[68:71], v[174:177], v[216:219], v[68:71]
	s_barrier
	s_mov_b32 m0, s45
	v_lshl_add_u64 v[178:179], v[178:179], 0, s[96:97]
	s_add_u32 s26, s26, 0x40080
	ds_read_b128 v[188:191], v165 offset:49152
	ds_read_b128 v[192:195], v165 offset:50176
	ds_read_b128 v[196:199], v165 offset:51200
	ds_read_b128 v[200:203], v165 offset:52224
	ds_read_b128 v[204:207], v165 offset:53248
	ds_read_b128 v[208:211], v165 offset:54272
	ds_read_b128 v[212:215], v165 offset:55296
	ds_read_b128 v[216:219], v165 offset:56320
	global_load_lds_dwordx4 v[178:179], off
	v_lshl_add_u64 v[178:179], v[220:221], 0, s[96:97]
	s_mov_b32 m0, s46
	s_addc_u32 s27, s27, 0
	global_load_lds_dwordx4 v[178:179], off
	v_lshl_add_u64 v[178:179], s[26:27], 0, v[2:3]
	s_mov_b32 m0, s50
	s_nop 0
	global_load_lds_dwordx4 v[178:179], off
	v_lshl_add_u64 v[178:179], s[26:27], 0, v[0:1]
	s_mov_b32 m0, s51
	s_nop 0
	global_load_lds_dwordx4 v[178:179], off
	v_lshl_add_u64 v[178:179], v[222:223], 0, s[96:97]
	s_mov_b32 m0, s47
	s_nop 0
	global_load_lds_dwordx4 v[178:179], off
	v_lshl_add_u64 v[178:179], v[224:225], 0, s[96:97]
	s_mov_b32 m0, s48
	s_nop 0
	global_load_lds_dwordx4 v[178:179], off
	s_waitcnt vmcnt(8)
	s_waitcnt lgkmcnt(0)
	s_barrier
	s_waitcnt lgkmcnt(0)
	v_mfma_f32_16x16x32_bf16 v[64:67], v[132:135], v[188:191], v[64:67]
	v_mfma_f32_16x16x32_bf16 v[56:59], v[150:153], v[188:191], v[56:59]
	v_mfma_f32_16x16x32_bf16 v[48:51], v[132:135], v[196:199], v[48:51]
	v_mfma_f32_16x16x32_bf16 v[40:43], v[150:153], v[196:199], v[40:43]
	v_mfma_f32_16x16x32_bf16 v[32:35], v[132:135], v[204:207], v[32:35]
	v_mfma_f32_16x16x32_bf16 v[24:27], v[150:153], v[204:207], v[24:27]
	v_mfma_f32_16x16x32_bf16 v[16:19], v[132:135], v[212:215], v[16:19]
	v_mfma_f32_16x16x32_bf16 v[8:11], v[150:153], v[212:215], v[8:11]
	v_mfma_f32_16x16x32_bf16 v[64:67], v[146:149], v[192:195], v[64:67]
	v_mfma_f32_16x16x32_bf16 v[56:59], v[154:157], v[192:195], v[56:59]
	v_mfma_f32_16x16x32_bf16 v[48:51], v[146:149], v[200:203], v[48:51]
	v_mfma_f32_16x16x32_bf16 v[40:43], v[154:157], v[200:203], v[40:43]
	v_mfma_f32_16x16x32_bf16 v[32:35], v[146:149], v[208:211], v[32:35]
	v_mfma_f32_16x16x32_bf16 v[24:27], v[154:157], v[208:211], v[24:27]
	v_mfma_f32_16x16x32_bf16 v[16:19], v[146:149], v[216:219], v[16:19]
	v_mfma_f32_16x16x32_bf16 v[8:11], v[154:157], v[216:219], v[8:11]
	v_mfma_f32_16x16x32_bf16 v[60:63], v[158:161], v[188:191], v[60:63]
	v_mfma_f32_16x16x32_bf16 v[52:55], v[170:173], v[188:191], v[52:55]
	v_mfma_f32_16x16x32_bf16 v[44:47], v[158:161], v[196:199], v[44:47]
	v_mfma_f32_16x16x32_bf16 v[36:39], v[170:173], v[196:199], v[36:39]
	v_mfma_f32_16x16x32_bf16 v[28:31], v[158:161], v[204:207], v[28:31]
	v_mfma_f32_16x16x32_bf16 v[20:23], v[170:173], v[204:207], v[20:23]
	v_mfma_f32_16x16x32_bf16 v[12:15], v[158:161], v[212:215], v[12:15]
	v_mfma_f32_16x16x32_bf16 v[4:7], v[170:173], v[212:215], v[4:7]
	v_mfma_f32_16x16x32_bf16 v[60:63], v[166:169], v[192:195], v[60:63]
	v_mfma_f32_16x16x32_bf16 v[52:55], v[174:177], v[192:195], v[52:55]
	v_mfma_f32_16x16x32_bf16 v[44:47], v[166:169], v[200:203], v[44:47]
	v_mfma_f32_16x16x32_bf16 v[36:39], v[174:177], v[200:203], v[36:39]
	v_mfma_f32_16x16x32_bf16 v[28:31], v[166:169], v[208:211], v[28:31]
	v_mfma_f32_16x16x32_bf16 v[20:23], v[174:177], v[208:211], v[20:23]
	v_mfma_f32_16x16x32_bf16 v[12:15], v[166:169], v[216:219], v[12:15]
	v_mfma_f32_16x16x32_bf16 v[4:7], v[174:177], v[216:219], v[4:7]
	s_barrier
	s_add_i32 s57, s57, 2
	s_add_u32 s24, s24, 0x100
	s_addc_u32 s25, s25, 0
	s_add_u32 s55, s55, 0x100
	s_addc_u32 s56, s56, 0
; #define PG8_STAGE(bufoff, gbase, voff) do { _Pragma("unroll") for (int _i = 0; _i < 2; ++_i) \
;         __builtin_amdgcn_global_load_lds((const unsigned*)((const char*)(gbase) + (voff)[_i]), (PG8_LAS unsigned*)(lds + (bufoff) + ldsw + _i * 8192), 16, 0, 0); } while (0)
; #define PG8_LDA(dst, b, h) do { _Pragma("unroll") for (int m = 0; m < 4; ++m) _Pragma("unroll") for (int k = 0; k < 2; ++k) dst[m][k] = *(const PG8_LAS bf16x8*)(lds + PG8_SA(b, h) + aoff + m * 2048 + k * 1024); } while (0)
; #define PG8_LDB(dst, b, h) do { _Pragma("unroll") for (int n = 0; n < 2; ++n) _Pragma("unroll") for (int k = 0; k < 2; ++k) dst[n][k] = *(const PG8_LAS bf16x8*)(lds + PG8_SB(b, h) + boff + n * 2048 + k * 1024); } while (0)
; #define PG8_MMA(ai, bj, At, Bt) do { __builtin_amdgcn_s_setprio(1); _Pragma("unroll") for (int m = 0; m < 4; ++m) _Pragma("unroll") for (int n = 0; n < 2; ++n) _Pragma("unroll") for (int k = 0; k < 2; ++k) \
;         acc[ai][bj][m][n] = __builtin_amdgcn_mfma_f32_16x16x32_bf16(Bt[n][k], At[m][k], acc[ai][bj][m][n], 0, 0, 0); __builtin_amdgcn_s_setprio(0); } while (0)
; #define PG8_WAIT_V(n) asm volatile("s_waitcnt vmcnt(" #n ")" ::: "memory")
; #define PG8_WAIT_L(n) asm volatile("s_waitcnt lgkmcnt(" #n ")" ::: "memory")
; #define PG8_BAR __builtin_amdgcn_s_barrier()
; template <class Epi, class Sched, bool ALIGN_EPI = false, bool SP2 = false>
; __device__ __forceinline__ void gemm_phase(PG8_LAS unsigned char* lds, const Gemm g, const Sched& S, const Epi& E, const int tid_) {
;     ...
;             const char* a1 = cA + (size_t)(t + 1) * kstep;
;             const char* a2 = last ? nA : cA + (size_t)(t + 2) * kstep; const char* b2 = last ? nB : cB + (size_t)(t + 2) * kstep;
;             const char* a3 = a2 + kstep; const char* b3 = b2 + kstep;
;             if (last && has_next) S.a_ready(nxt);
;             if constexpr (SP2) {
;             PG8_LDB(B0, 0, 0); PG8_LDB(B1, 0, 1); PG8_SCHED; PG8_LDA(At, 0, 0); PG8_STAGE(PG8_SA(1, 1), a1 + hstep, voffA);
;             PG8_WAIT_V(8); PG8_WAIT_L(0); PG8_BAR; PG8_MMA(0, 0, At, B0); PG8_MMA(0, 1, At, B1); PG8_BAR; PG8_SCHED;
;             PG8_LDA(At, 0, 1); PG8_STAGE(PG8_SB(0, 0), b2, voffB); PG8_STAGE(PG8_SB(0, 1), b2 + hstepB, voffB); PG8_STAGE(PG8_SA(0, 0), a2, voffA);
;             PG8_WAIT_V(8); PG8_WAIT_L(0); PG8_BAR; PG8_MMA(1, 0, At, B0); PG8_MMA(1, 1, At, B1); PG8_BAR; PG8_SCHED;
.LBB0_24:
	v_add_u32_e32 v154, s23, v163
	v_add_u32_e32 v174, s37, v163
	ds_read_b128 v[132:135], v154
	ds_read_b128 v[146:149], v154 offset:1024
	ds_read_b128 v[150:153], v154 offset:2048
	ds_read_b128 v[154:157], v154 offset:3072
	ds_read_b128 v[158:161], v174
	ds_read_b128 v[166:169], v174 offset:1024
	ds_read_b128 v[170:173], v174 offset:2048
	ds_read_b128 v[174:177], v174 offset:3072
	s_add_u32 s26, s24, 0xfffc0080
	s_addc_u32 s27, s25, -1
	s_cmp_eq_u32 s57, 12
	s_cselect_b32 s29, s2, s27
	s_cselect_b32 s28, s3, s26
	s_cselect_b32 s27, s15, s56
	s_cselect_b32 s26, s17, s55
	v_lshl_add_u64 v[178:179], s[24:25], 0, v[142:143]
	s_add_i32 m0, s40, 0xc000
	ds_read_b128 v[188:191], v165
	ds_read_b128 v[192:195], v165 offset:1024
	ds_read_b128 v[196:199], v165 offset:2048
	ds_read_b128 v[200:203], v165 offset:3072
	ds_read_b128 v[204:207], v165 offset:4096
	ds_read_b128 v[208:211], v165 offset:5120
	ds_read_b128 v[212:215], v165 offset:6144
	ds_read_b128 v[216:219], v165 offset:7168
	global_load_lds_dwordx4 v[178:179], off
	v_lshl_add_u64 v[178:179], s[24:25], 0, v[144:145]
	s_add_i32 m0, s40, 0xe000
	s_nop 0
	global_load_lds_dwordx4 v[178:179], off
	s_waitcnt vmcnt(8)
	s_waitcnt lgkmcnt(0)
	s_barrier
	s_waitcnt lgkmcnt(0)
	v_mfma_f32_16x16x32_bf16 v[128:131], v[132:135], v[188:191], v[128:131]
	v_mfma_f32_16x16x32_bf16 v[120:123], v[150:153], v[188:191], v[120:123]
	v_mfma_f32_16x16x32_bf16 v[112:115], v[132:135], v[196:199], v[112:115]
	v_mfma_f32_16x16x32_bf16 v[104:107], v[150:153], v[196:199], v[104:107]
	v_mfma_f32_16x16x32_bf16 v[96:99], v[132:135], v[204:207], v[96:99]
	v_mfma_f32_16x16x32_bf16 v[88:91], v[150:153], v[204:207], v[88:91]
	v_mfma_f32_16x16x32_bf16 v[80:83], v[132:135], v[212:215], v[80:83]
	v_mfma_f32_16x16x32_bf16 v[72:75], v[150:153], v[212:215], v[72:75]
	v_mfma_f32_16x16x32_bf16 v[128:131], v[146:149], v[192:195], v[128:131]
	v_mfma_f32_16x16x32_bf16 v[120:123], v[154:157], v[192:195], v[120:123]
	v_mfma_f32_16x16x32_bf16 v[112:115], v[146:149], v[200:203], v[112:115]
	v_mfma_f32_16x16x32_bf16 v[104:107], v[154:157], v[200:203], v[104:107]
	v_mfma_f32_16x16x32_bf16 v[96:99], v[146:149], v[208:211], v[96:99]
	v_mfma_f32_16x16x32_bf16 v[88:91], v[154:157], v[208:211], v[88:91]
	v_mfma_f32_16x16x32_bf16 v[80:83], v[146:149], v[216:219], v[80:83]
	v_mfma_f32_16x16x32_bf16 v[72:75], v[154:157], v[216:219], v[72:75]
	v_mfma_f32_16x16x32_bf16 v[124:127], v[158:161], v[188:191], v[124:127]
	v_mfma_f32_16x16x32_bf16 v[116:119], v[170:173], v[188:191], v[116:119]
	v_mfma_f32_16x16x32_bf16 v[108:111], v[158:161], v[196:199], v[108:111]
	v_mfma_f32_16x16x32_bf16 v[100:103], v[170:173], v[196:199], v[100:103]
	v_mfma_f32_16x16x32_bf16 v[92:95], v[158:161], v[204:207], v[92:95]
	v_mfma_f32_16x16x32_bf16 v[84:87], v[170:173], v[204:207], v[84:87]
	v_mfma_f32_16x16x32_bf16 v[76:79], v[158:161], v[212:215], v[76:79]
	v_mfma_f32_16x16x32_bf16 v[68:71], v[170:173], v[212:215], v[68:71]
	v_mfma_f32_16x16x32_bf16 v[124:127], v[166:169], v[192:195], v[124:127]
	v_mfma_f32_16x16x32_bf16 v[116:119], v[174:177], v[192:195], v[116:119]
	v_mfma_f32_16x16x32_bf16 v[108:111], v[166:169], v[200:203], v[108:111]
	v_mfma_f32_16x16x32_bf16 v[100:103], v[174:177], v[200:203], v[100:103]
	v_mfma_f32_16x16x32_bf16 v[92:95], v[166:169], v[208:211], v[92:95]
	v_mfma_f32_16x16x32_bf16 v[84:87], v[174:177], v[208:211], v[84:87]
	v_mfma_f32_16x16x32_bf16 v[76:79], v[166:169], v[216:219], v[76:79]
	v_mfma_f32_16x16x32_bf16 v[68:71], v[174:177], v[216:219], v[68:71]
	s_barrier
	s_mov_b32 m0, s35
	v_lshl_add_u64 v[178:179], s[26:27], 0, v[2:3]
	s_add_u32 s58, s26, 0x40000
	ds_read_b128 v[188:191], v165 offset:16384
	ds_read_b128 v[192:195], v165 offset:17408
	ds_read_b128 v[196:199], v165 offset:18432
	ds_read_b128 v[200:203], v165 offset:19456
	ds_read_b128 v[204:207], v165 offset:20480
	ds_read_b128 v[208:211], v165 offset:21504
	ds_read_b128 v[212:215], v165 offset:22528
	ds_read_b128 v[216:219], v165 offset:23552
	global_load_lds_dwordx4 v[178:179], off
	v_lshl_add_u64 v[220:221], s[26:27], 0, v[0:1]
	s_mov_b32 m0, s36
	s_addc_u32 s59, s27, 0
	global_load_lds_dwordx4 v[220:221], off
	v_lshl_add_u64 v[222:223], s[58:59], 0, v[2:3]
	s_mov_b32 m0, s38
	v_lshl_add_u64 v[224:225], s[28:29], 0, v[136:137]
	global_load_lds_dwordx4 v[222:223], off
	v_lshl_add_u64 v[222:223], s[58:59], 0, v[0:1]
	s_mov_b32 m0, s39
	s_nop 0
	global_load_lds_dwordx4 v[222:223], off
	v_lshl_add_u64 v[222:223], s[28:29], 0, v[138:139]
	s_mov_b32 m0, s40
	s_nop 0
	global_load_lds_dwordx4 v[222:223], off
	s_mov_b32 m0, s41
	s_nop 0
	global_load_lds_dwordx4 v[224:225], off
	s_waitcnt vmcnt(8)
	s_waitcnt lgkmcnt(0)
	s_barrier
; #define PG8_STAGE(bufoff, gbase, voff) do { _Pragma("unroll") for (int _i = 0; _i < 2; ++_i) \
;         __builtin_amdgcn_global_load_lds((const unsigned*)((const char*)(gbase) + (voff)[_i]), (PG8_LAS unsigned*)(lds + (bufoff) + ldsw + _i * 8192), 16, 0, 0); } while (0)
; #define PG8_LDA(dst, b, h) do { _Pragma("unroll") for (int m = 0; m < 4; ++m) _Pragma("unroll") for (int k = 0; k < 2; ++k) dst[m][k] = *(const PG8_LAS bf16x8*)(lds + PG8_SA(b, h) + aoff + m * 2048 + k * 1024); } while (0)
; #define PG8_LDB(dst, b, h) do { _Pragma("unroll") for (int n = 0; n < 2; ++n) _Pragma("unroll") for (int k = 0; k < 2; ++k) dst[n][k] = *(const PG8_LAS bf16x8*)(lds + PG8_SB(b, h) + boff + n * 2048 + k * 1024); } while (0)
; #define PG8_MMA(ai, bj, At, Bt) do { __builtin_amdgcn_s_setprio(1); _Pragma("unroll") for (int m = 0; m < 4; ++m) _Pragma("unroll") for (int n = 0; n < 2; ++n) _Pragma("unroll") for (int k = 0; k < 2; ++k) \
;         acc[ai][bj][m][n] = __builtin_amdgcn_mfma_f32_16x16x32_bf16(Bt[n][k], At[m][k], acc[ai][bj][m][n], 0, 0, 0); __builtin_amdgcn_s_setprio(0); } while (0)
; #define PG8_WAIT_V(n) asm volatile("s_waitcnt vmcnt(" #n ")" ::: "memory")
; #define PG8_WAIT_L(n) asm volatile("s_waitcnt lgkmcnt(" #n ")" ::: "memory")
; #define PG8_BAR __builtin_amdgcn_s_barrier()
; #define PG8_SCHED __builtin_amdgcn_sched_barrier(0)
; template <class Epi, class Sched, bool ALIGN_EPI = false, bool SP2 = false>
; __device__ __forceinline__ void gemm_phase(PG8_LAS unsigned char* lds, const Gemm g, const Sched& S, const Epi& E, const int tid_) {
;     ...
;             PG8_WAIT_V(8); PG8_WAIT_L(0); PG8_BAR; PG8_MMA(1, 0, At, B0); PG8_MMA(1, 1, At, B1); PG8_BAR; PG8_SCHED;
;             PG8_LDB(B0, 1, 0); PG8_LDB(B1, 1, 1); PG8_SCHED; PG8_LDA(At, 1, 0); PG8_STAGE(PG8_SA(0, 1), a2 + hstep, voffA);
;             PG8_WAIT_V(8); PG8_WAIT_L(0); PG8_BAR; PG8_MMA(0, 0, At, B0); PG8_MMA(0, 1, At, B1); PG8_BAR; PG8_SCHED;
	s_waitcnt lgkmcnt(0)
	v_mfma_f32_16x16x32_bf16 v[64:67], v[132:135], v[188:191], v[64:67]
	v_mfma_f32_16x16x32_bf16 v[56:59], v[150:153], v[188:191], v[56:59]
	v_mfma_f32_16x16x32_bf16 v[48:51], v[132:135], v[196:199], v[48:51]
	v_mfma_f32_16x16x32_bf16 v[40:43], v[150:153], v[196:199], v[40:43]
	v_mfma_f32_16x16x32_bf16 v[32:35], v[132:135], v[204:207], v[32:35]
	v_mfma_f32_16x16x32_bf16 v[24:27], v[150:153], v[204:207], v[24:27]
	v_mfma_f32_16x16x32_bf16 v[16:19], v[132:135], v[212:215], v[16:19]
	v_mfma_f32_16x16x32_bf16 v[8:11], v[150:153], v[212:215], v[8:11]
	v_mfma_f32_16x16x32_bf16 v[64:67], v[146:149], v[192:195], v[64:67]
	v_mfma_f32_16x16x32_bf16 v[56:59], v[154:157], v[192:195], v[56:59]
	v_mfma_f32_16x16x32_bf16 v[48:51], v[146:149], v[200:203], v[48:51]
	v_mfma_f32_16x16x32_bf16 v[40:43], v[154:157], v[200:203], v[40:43]
	v_mfma_f32_16x16x32_bf16 v[32:35], v[146:149], v[208:211], v[32:35]
	v_mfma_f32_16x16x32_bf16 v[24:27], v[154:157], v[208:211], v[24:27]
	v_mfma_f32_16x16x32_bf16 v[16:19], v[146:149], v[216:219], v[16:19]
	v_mfma_f32_16x16x32_bf16 v[8:11], v[154:157], v[216:219], v[8:11]
	v_mfma_f32_16x16x32_bf16 v[60:63], v[158:161], v[188:191], v[60:63]
	v_mfma_f32_16x16x32_bf16 v[52:55], v[170:173], v[188:191], v[52:55]
	v_mfma_f32_16x16x32_bf16 v[44:47], v[158:161], v[196:199], v[44:47]
	v_mfma_f32_16x16x32_bf16 v[36:39], v[170:173], v[196:199], v[36:39]
	v_mfma_f32_16x16x32_bf16 v[28:31], v[158:161], v[204:207], v[28:31]
	v_mfma_f32_16x16x32_bf16 v[20:23], v[170:173], v[204:207], v[20:23]
	v_mfma_f32_16x16x32_bf16 v[12:15], v[158:161], v[212:215], v[12:15]
	v_mfma_f32_16x16x32_bf16 v[4:7], v[170:173], v[212:215], v[4:7]
	v_mfma_f32_16x16x32_bf16 v[60:63], v[166:169], v[192:195], v[60:63]
	v_mfma_f32_16x16x32_bf16 v[52:55], v[174:177], v[192:195], v[52:55]
	v_mfma_f32_16x16x32_bf16 v[44:47], v[166:169], v[200:203], v[44:47]
	v_mfma_f32_16x16x32_bf16 v[36:39], v[174:177], v[200:203], v[36:39]
	v_mfma_f32_16x16x32_bf16 v[28:31], v[166:169], v[208:211], v[28:31]
	v_mfma_f32_16x16x32_bf16 v[20:23], v[174:177], v[208:211], v[20:23]
	v_mfma_f32_16x16x32_bf16 v[12:15], v[166:169], v[216:219], v[12:15]
	v_mfma_f32_16x16x32_bf16 v[4:7], v[174:177], v[216:219], v[4:7]
	s_barrier
	v_add_u32_e32 v154, s44, v163
	v_add_u32_e32 v174, s49, v163
	ds_read_b128 v[132:135], v154
	ds_read_b128 v[146:149], v154 offset:1024
	ds_read_b128 v[150:153], v154 offset:2048
	ds_read_b128 v[154:157], v154 offset:3072
	ds_read_b128 v[158:161], v174
	ds_read_b128 v[166:169], v174 offset:1024
	ds_read_b128 v[170:173], v174 offset:2048
	ds_read_b128 v[174:177], v174 offset:3072
	s_add_u32 s28, s28, 0x40000
	s_addc_u32 s29, s29, 0
	s_mov_b32 m0, s42
	v_lshl_add_u64 v[226:227], s[28:29], 0, v[138:139]
	ds_read_b128 v[188:191], v165 offset:32768
	ds_read_b128 v[192:195], v165 offset:33792
	ds_read_b128 v[196:199], v165 offset:34816
	ds_read_b128 v[200:203], v165 offset:35840
	ds_read_b128 v[204:207], v165 offset:36864
	ds_read_b128 v[208:211], v165 offset:37888
	ds_read_b128 v[212:215], v165 offset:38912
	ds_read_b128 v[216:219], v165 offset:39936
	global_load_lds_dwordx4 v[226:227], off
	v_lshl_add_u64 v[226:227], s[28:29], 0, v[136:137]
	s_mov_b32 m0, s43
	s_nop 0
	global_load_lds_dwordx4 v[226:227], off
	s_waitcnt vmcnt(8)
	s_waitcnt lgkmcnt(0)
	s_barrier
	s_waitcnt lgkmcnt(0)
	v_mfma_f32_16x16x32_bf16 v[128:131], v[132:135], v[188:191], v[128:131]
	v_mfma_f32_16x16x32_bf16 v[120:123], v[150:153], v[188:191], v[120:123]
	v_mfma_f32_16x16x32_bf16 v[112:115], v[132:135], v[196:199], v[112:115]
	v_mfma_f32_16x16x32_bf16 v[104:107], v[150:153], v[196:199], v[104:107]
	v_mfma_f32_16x16x32_bf16 v[96:99], v[132:135], v[204:207], v[96:99]
	v_mfma_f32_16x16x32_bf16 v[88:91], v[150:153], v[204:207], v[88:91]
	v_mfma_f32_16x16x32_bf16 v[80:83], v[132:135], v[212:215], v[80:83]
	v_mfma_f32_16x16x32_bf16 v[72:75], v[150:153], v[212:215], v[72:75]
	v_mfma_f32_16x16x32_bf16 v[128:131], v[146:149], v[192:195], v[128:131]
	v_mfma_f32_16x16x32_bf16 v[120:123], v[154:157], v[192:195], v[120:123]
	v_mfma_f32_16x16x32_bf16 v[112:115], v[146:149], v[200:203], v[112:115]
	v_mfma_f32_16x16x32_bf16 v[104:107], v[154:157], v[200:203], v[104:107]
	v_mfma_f32_16x16x32_bf16 v[96:99], v[146:149], v[208:211], v[96:99]
	v_mfma_f32_16x16x32_bf16 v[88:91], v[154:157], v[208:211], v[88:91]
	v_mfma_f32_16x16x32_bf16 v[80:83], v[146:149], v[216:219], v[80:83]
	v_mfma_f32_16x16x32_bf16 v[72:75], v[154:157], v[216:219], v[72:75]
	v_mfma_f32_16x16x32_bf16 v[124:127], v[158:161], v[188:191], v[124:127]
	v_mfma_f32_16x16x32_bf16 v[116:119], v[170:173], v[188:191], v[116:119]
	v_mfma_f32_16x16x32_bf16 v[108:111], v[158:161], v[196:199], v[108:111]
	v_mfma_f32_16x16x32_bf16 v[100:103], v[170:173], v[196:199], v[100:103]
	v_mfma_f32_16x16x32_bf16 v[92:95], v[158:161], v[204:207], v[92:95]
	v_mfma_f32_16x16x32_bf16 v[84:87], v[170:173], v[204:207], v[84:87]
	v_mfma_f32_16x16x32_bf16 v[76:79], v[158:161], v[212:215], v[76:79]
	v_mfma_f32_16x16x32_bf16 v[68:71], v[170:173], v[212:215], v[68:71]
	v_mfma_f32_16x16x32_bf16 v[124:127], v[166:169], v[192:195], v[124:127]
	v_mfma_f32_16x16x32_bf16 v[116:119], v[174:177], v[192:195], v[116:119]
	v_mfma_f32_16x16x32_bf16 v[108:111], v[166:169], v[200:203], v[108:111]
	v_mfma_f32_16x16x32_bf16 v[100:103], v[174:177], v[200:203], v[100:103]
	v_mfma_f32_16x16x32_bf16 v[92:95], v[166:169], v[208:211], v[92:95]
	v_mfma_f32_16x16x32_bf16 v[84:87], v[174:177], v[208:211], v[84:87]
	v_mfma_f32_16x16x32_bf16 v[76:79], v[166:169], v[216:219], v[76:79]
	v_mfma_f32_16x16x32_bf16 v[68:71], v[174:177], v[216:219], v[68:71]
	s_barrier
; #define PG8_STAGE(bufoff, gbase, voff) do { _Pragma("unroll") for (int _i = 0; _i < 2; ++_i) \
;         __builtin_amdgcn_global_load_lds((const unsigned*)((const char*)(gbase) + (voff)[_i]), (PG8_LAS unsigned*)(lds + (bufoff) + ldsw + _i * 8192), 16, 0, 0); } while (0)
; #define PG8_LDA(dst, b, h) do { _Pragma("unroll") for (int m = 0; m < 4; ++m) _Pragma("unroll") for (int k = 0; k < 2; ++k) dst[m][k] = *(const PG8_LAS bf16x8*)(lds + PG8_SA(b, h) + aoff + m * 2048 + k * 1024); } while (0)
; #define PG8_MMA(ai, bj, At, Bt) do { __builtin_amdgcn_s_setprio(1); _Pragma("unroll") for (int m = 0; m < 4; ++m) _Pragma("unroll") for (int n = 0; n < 2; ++n) _Pragma("unroll") for (int k = 0; k < 2; ++k) \
;         acc[ai][bj][m][n] = __builtin_amdgcn_mfma_f32_16x16x32_bf16(Bt[n][k], At[m][k], acc[ai][bj][m][n], 0, 0, 0); __builtin_amdgcn_s_setprio(0); } while (0)
; #define PG8_WAIT_V(n) asm volatile("s_waitcnt vmcnt(" #n ")" ::: "memory")
; #define PG8_WAIT_L(n) asm volatile("s_waitcnt lgkmcnt(" #n ")" ::: "memory")
; #define PG8_BAR __builtin_amdgcn_s_barrier()
; #define PG8_SCHED __builtin_amdgcn_sched_barrier(0)
; template <class Epi, class Sched, bool ALIGN_EPI = false, bool SP2 = false>
; __device__ __forceinline__ void gemm_phase(PG8_LAS unsigned char* lds, const Gemm g, const Sched& S, const Epi& E, const int tid_) {
;     ...
;             PG8_LDA(At, 1, 1); PG8_STAGE(PG8_SB(1, 0), b3, voffB); PG8_STAGE(PG8_SB(1, 1), b3 + hstepB, voffB); PG8_STAGE(PG8_SA(1, 0), a3, voffA);
;             PG8_WAIT_V(8); PG8_WAIT_L(0); PG8_BAR; PG8_MMA(1, 0, At, B0); PG8_MMA(1, 1, At, B1); PG8_BAR; PG8_SCHED;
;     ...
;         if constexpr (ALIGN_EPI) { if (wr == 0) PG8_BAR; }
	s_mov_b32 m0, s45
	v_lshl_add_u64 v[178:179], v[178:179], 0, s[96:97]
	s_add_u32 s26, s26, 0x40080
	ds_read_b128 v[188:191], v165 offset:49152
	ds_read_b128 v[192:195], v165 offset:50176
	ds_read_b128 v[196:199], v165 offset:51200
	ds_read_b128 v[200:203], v165 offset:52224
	ds_read_b128 v[204:207], v165 offset:53248
	ds_read_b128 v[208:211], v165 offset:54272
	ds_read_b128 v[212:215], v165 offset:55296
	ds_read_b128 v[216:219], v165 offset:56320
	global_load_lds_dwordx4 v[178:179], off
	v_lshl_add_u64 v[178:179], v[220:221], 0, s[96:97]
	s_mov_b32 m0, s46
	s_addc_u32 s27, s27, 0
	global_load_lds_dwordx4 v[178:179], off
	v_lshl_add_u64 v[178:179], s[26:27], 0, v[2:3]
	s_mov_b32 m0, s50
	s_nop 0
	global_load_lds_dwordx4 v[178:179], off
	v_lshl_add_u64 v[178:179], s[26:27], 0, v[0:1]
	s_mov_b32 m0, s51
	s_nop 0
	global_load_lds_dwordx4 v[178:179], off
	v_lshl_add_u64 v[178:179], v[222:223], 0, s[96:97]
	s_mov_b32 m0, s47
	s_nop 0
	global_load_lds_dwordx4 v[178:179], off
	v_lshl_add_u64 v[178:179], v[224:225], 0, s[96:97]
	s_mov_b32 m0, s48
	s_nop 0
	global_load_lds_dwordx4 v[178:179], off
	s_waitcnt vmcnt(8)
	s_waitcnt lgkmcnt(0)
	s_barrier
	s_waitcnt lgkmcnt(0)
	v_mfma_f32_16x16x32_bf16 v[64:67], v[132:135], v[188:191], v[64:67]
	v_mfma_f32_16x16x32_bf16 v[56:59], v[150:153], v[188:191], v[56:59]
	v_mfma_f32_16x16x32_bf16 v[48:51], v[132:135], v[196:199], v[48:51]
	v_mfma_f32_16x16x32_bf16 v[40:43], v[150:153], v[196:199], v[40:43]
	v_mfma_f32_16x16x32_bf16 v[32:35], v[132:135], v[204:207], v[32:35]
	v_mfma_f32_16x16x32_bf16 v[24:27], v[150:153], v[204:207], v[24:27]
	v_mfma_f32_16x16x32_bf16 v[16:19], v[132:135], v[212:215], v[16:19]
	v_mfma_f32_16x16x32_bf16 v[8:11], v[150:153], v[212:215], v[8:11]
	v_mfma_f32_16x16x32_bf16 v[64:67], v[146:149], v[192:195], v[64:67]
	v_mfma_f32_16x16x32_bf16 v[56:59], v[154:157], v[192:195], v[56:59]
	v_mfma_f32_16x16x32_bf16 v[48:51], v[146:149], v[200:203], v[48:51]
	v_mfma_f32_16x16x32_bf16 v[40:43], v[154:157], v[200:203], v[40:43]
	v_mfma_f32_16x16x32_bf16 v[32:35], v[146:149], v[208:211], v[32:35]
	v_mfma_f32_16x16x32_bf16 v[24:27], v[154:157], v[208:211], v[24:27]
	v_mfma_f32_16x16x32_bf16 v[16:19], v[146:149], v[216:219], v[16:19]
	v_mfma_f32_16x16x32_bf16 v[8:11], v[154:157], v[216:219], v[8:11]
	v_mfma_f32_16x16x32_bf16 v[60:63], v[158:161], v[188:191], v[60:63]
	v_mfma_f32_16x16x32_bf16 v[52:55], v[170:173], v[188:191], v[52:55]
	v_mfma_f32_16x16x32_bf16 v[44:47], v[158:161], v[196:199], v[44:47]
	v_mfma_f32_16x16x32_bf16 v[36:39], v[170:173], v[196:199], v[36:39]
	v_mfma_f32_16x16x32_bf16 v[28:31], v[158:161], v[204:207], v[28:31]
	v_mfma_f32_16x16x32_bf16 v[20:23], v[170:173], v[204:207], v[20:23]
	v_mfma_f32_16x16x32_bf16 v[12:15], v[158:161], v[212:215], v[12:15]
	v_mfma_f32_16x16x32_bf16 v[4:7], v[170:173], v[212:215], v[4:7]
	v_mfma_f32_16x16x32_bf16 v[60:63], v[166:169], v[192:195], v[60:63]
	v_mfma_f32_16x16x32_bf16 v[52:55], v[174:177], v[192:195], v[52:55]
	v_mfma_f32_16x16x32_bf16 v[44:47], v[166:169], v[200:203], v[44:47]
	v_mfma_f32_16x16x32_bf16 v[36:39], v[174:177], v[200:203], v[36:39]
	v_mfma_f32_16x16x32_bf16 v[28:31], v[166:169], v[208:211], v[28:31]
	v_mfma_f32_16x16x32_bf16 v[20:23], v[174:177], v[208:211], v[20:23]
	v_mfma_f32_16x16x32_bf16 v[12:15], v[166:169], v[216:219], v[12:15]
	v_mfma_f32_16x16x32_bf16 v[4:7], v[174:177], v[216:219], v[4:7]
	s_barrier
	s_add_i32 s57, s57, 2
	s_add_u32 s24, s24, 0x100
	s_addc_u32 s25, s25, 0
	s_add_u32 s55, s55, 0x100
	s_addc_u32 s56, s56, 0
	s_cmp_gt_u32 s57, 13
	s_cbranch_scc0 .LBB0_24
	s_and_b64 vcc, exec, s[12:13]
	s_cbranch_vccz .LBB0_27
	s_barrier

; #define PG8_STAGE(bufoff, gbase, voff) do { _Pragma("unroll") for (int _i = 0; _i < 2; ++_i) \
;         __builtin_amdgcn_global_load_lds((const unsigned*)((const char*)(gbase) + (voff)[_i]), (PG8_LAS unsigned*)(lds + (bufoff) + ldsw + _i * 8192), 16, 0, 0); } while (0)
; #define PG8_LDA(dst, b, h) do { _Pragma("unroll") for (int m = 0; m < 4; ++m) _Pragma("unroll") for (int k = 0; k < 2; ++k) dst[m][k] = *(const PG8_LAS bf16x8*)(lds + PG8_SA(b, h) + aoff + m * 2048 + k * 1024); } while (0)
; #define PG8_LDB(dst, b, h) do { _Pragma("unroll") for (int n = 0; n < 2; ++n) _Pragma("unroll") for (int k = 0; k < 2; ++k) dst[n][k] = *(const PG8_LAS bf16x8*)(lds + PG8_SB(b, h) + boff + n * 2048 + k * 1024); } while (0)
; #define PG8_MMA(ai, bj, At, Bt) do { __builtin_amdgcn_s_setprio(1); _Pragma("unroll") for (int m = 0; m < 4; ++m) _Pragma("unroll") for (int n = 0; n < 2; ++n) _Pragma("unroll") for (int k = 0; k < 2; ++k) \
;         acc[ai][bj][m][n] = __builtin_amdgcn_mfma_f32_16x16x32_bf16(Bt[n][k], At[m][k], acc[ai][bj][m][n], 0, 0, 0); __builtin_amdgcn_s_setprio(0); } while (0)
; #define PG8_WAIT_V(n) asm volatile("s_waitcnt vmcnt(" #n ")" ::: "memory")
; #define PG8_WAIT_L(n) asm volatile("s_waitcnt lgkmcnt(" #n ")" ::: "memory")
; #define PG8_BAR __builtin_amdgcn_s_barrier()
; #define PG8_SCHED __builtin_amdgcn_sched_barrier(0)
; template <class Epi, class Sched, bool ALIGN_EPI = false, bool SP2 = false>
; __device__ __forceinline__ void gemm_phase(PG8_LAS unsigned char* lds, const Gemm g, const Sched& S, const Epi& E, const int tid_) {
;     ...
;             PG8_LDB(B0, 0, 0); PG8_LDB(B1, 0, 1); PG8_SCHED; PG8_LDA(At, 0, 0); PG8_STAGE(PG8_SA(1, 1), a1 + hstep, voffA);
;             PG8_WAIT_V(8); PG8_WAIT_L(0); PG8_BAR; PG8_MMA(0, 0, At, B0); PG8_MMA(0, 1, At, B1); PG8_BAR; PG8_SCHED;
;             PG8_LDA(At, 0, 1); PG8_STAGE(PG8_SB(0, 0), b2, voffB); PG8_STAGE(PG8_SB(0, 1), b2 + hstepB, voffB); PG8_STAGE(PG8_SA(0, 0), a2, voffA);
;             PG8_WAIT_V(8); PG8_WAIT_L(0); PG8_BAR; PG8_MMA(1, 0, At, B0); PG8_MMA(1, 1, At, B1); PG8_BAR; PG8_SCHED;
.Lpeel2_mx0:
	s_waitcnt lgkmcnt(0)
	s_barrier
	s_waitcnt lgkmcnt(0)
	v_mfma_f32_16x16x32_bf16 v[144:147], v[12:15], v[164:167], 0
	v_mfma_f32_16x16x32_bf16 v[140:143], v[36:39], v[164:167], 0
	v_mfma_f32_16x16x32_bf16 v[128:131], v[12:15], v[198:201], 0
	v_mfma_f32_16x16x32_bf16 v[124:127], v[36:39], v[198:201], 0
	v_mfma_f32_16x16x32_bf16 v[112:115], v[12:15], v[206:209], 0
	v_mfma_f32_16x16x32_bf16 v[108:111], v[36:39], v[206:209], 0
	v_mfma_f32_16x16x32_bf16 v[96:99], v[12:15], v[214:217], 0
	v_mfma_f32_16x16x32_bf16 v[92:95], v[36:39], v[214:217], 0
	v_mfma_f32_16x16x32_bf16 v[144:147], v[16:19], v[168:171], v[144:147]
	v_mfma_f32_16x16x32_bf16 v[140:143], v[40:43], v[168:171], v[140:143]
	v_mfma_f32_16x16x32_bf16 v[128:131], v[16:19], v[202:205], v[128:131]
	v_mfma_f32_16x16x32_bf16 v[124:127], v[40:43], v[202:205], v[124:127]
	v_mfma_f32_16x16x32_bf16 v[112:115], v[16:19], v[210:213], v[112:115]
	v_mfma_f32_16x16x32_bf16 v[108:111], v[40:43], v[210:213], v[108:111]
	v_mfma_f32_16x16x32_bf16 v[96:99], v[16:19], v[218:221], v[96:99]
	v_mfma_f32_16x16x32_bf16 v[92:95], v[40:43], v[218:221], v[92:95]
	v_mfma_f32_16x16x32_bf16 v[136:139], v[148:151], v[164:167], 0
	v_mfma_f32_16x16x32_bf16 v[132:135], v[156:159], v[164:167], 0
	v_mfma_f32_16x16x32_bf16 v[120:123], v[148:151], v[198:201], 0
	v_mfma_f32_16x16x32_bf16 v[116:119], v[156:159], v[198:201], 0
	v_mfma_f32_16x16x32_bf16 v[104:107], v[148:151], v[206:209], 0
	v_mfma_f32_16x16x32_bf16 v[100:103], v[156:159], v[206:209], 0
	v_mfma_f32_16x16x32_bf16 v[88:91], v[148:151], v[214:217], 0
	v_mfma_f32_16x16x32_bf16 v[84:87], v[156:159], v[214:217], 0
	v_mfma_f32_16x16x32_bf16 v[136:139], v[152:155], v[168:171], v[136:139]
	v_mfma_f32_16x16x32_bf16 v[132:135], v[160:163], v[168:171], v[132:135]
	v_mfma_f32_16x16x32_bf16 v[120:123], v[152:155], v[202:205], v[120:123]
	v_mfma_f32_16x16x32_bf16 v[116:119], v[160:163], v[202:205], v[116:119]
	v_mfma_f32_16x16x32_bf16 v[104:107], v[152:155], v[210:213], v[104:107]
	v_mfma_f32_16x16x32_bf16 v[100:103], v[160:163], v[210:213], v[100:103]
	v_mfma_f32_16x16x32_bf16 v[88:91], v[152:155], v[218:221], v[88:91]
	v_mfma_f32_16x16x32_bf16 v[84:87], v[160:163], v[218:221], v[84:87]
	s_barrier
	s_mov_b32 m0, s62
	v_lshl_add_u64 v[194:195], s[52:53], 0, v[172:173]
	v_lshl_add_u64 v[222:223], s[52:53], 0, v[176:177]
	s_add_u32 s52, s52, s38
	ds_read_b128 v[164:167], v238 offset:16384
	ds_read_b128 v[168:171], v238 offset:17408
	ds_read_b128 v[198:201], v238 offset:18432
	ds_read_b128 v[202:205], v238 offset:19456
	ds_read_b128 v[206:209], v238 offset:20480
	ds_read_b128 v[210:213], v238 offset:21504
	ds_read_b128 v[214:217], v238 offset:22528
	ds_read_b128 v[218:221], v238 offset:23552
	global_load_lds_dwordx4 v[194:195], off
	s_mov_b32 m0, s63
	s_addc_u32 s53, s53, s39
	global_load_lds_dwordx4 v[222:223], off
	v_lshl_add_u64 v[224:225], s[52:53], 0, v[172:173]
	s_mov_b32 m0, s65
	v_lshl_add_u64 v[226:227], s[52:53], 0, v[176:177]
	global_load_lds_dwordx4 v[224:225], off
	s_mov_b32 m0, s66
	v_lshl_add_u64 v[228:229], s[10:11], 0, v[0:1]
	global_load_lds_dwordx4 v[226:227], off
	s_mov_b32 m0, s67
	v_lshl_add_u64 v[230:231], s[10:11], 0, v[174:175]
	global_load_lds_dwordx4 v[228:229], off
	s_mov_b32 m0, s68
	s_nop 0
	global_load_lds_dwordx4 v[230:231], off
	s_cmp_lg_u32 s86, 1
	s_cbranch_scc1 .Lpeel2_mx1
	s_waitcnt vmcnt(8)
.Lpeel2_mx1:
	s_waitcnt lgkmcnt(0)
	s_barrier
	s_waitcnt lgkmcnt(0)
	v_mfma_f32_16x16x32_bf16 v[80:83], v[12:15], v[164:167], 0
	v_mfma_f32_16x16x32_bf16 v[76:79], v[36:39], v[164:167], 0
	v_mfma_f32_16x16x32_bf16 v[64:67], v[12:15], v[198:201], 0
	v_mfma_f32_16x16x32_bf16 v[60:63], v[36:39], v[198:201], 0
	v_mfma_f32_16x16x32_bf16 v[48:51], v[12:15], v[206:209], 0
	v_mfma_f32_16x16x32_bf16 v[44:47], v[36:39], v[206:209], 0
	v_mfma_f32_16x16x32_bf16 v[12:15], v[12:15], v[214:217], 0
	v_mfma_f32_16x16x32_bf16 v[80:83], v[16:19], v[168:171], v[80:83]
	v_mfma_f32_16x16x32_bf16 v[76:79], v[40:43], v[168:171], v[76:79]
	v_mfma_f32_16x16x32_bf16 v[64:67], v[16:19], v[202:205], v[64:67]
	v_mfma_f32_16x16x32_bf16 v[60:63], v[40:43], v[202:205], v[60:63]
	v_mfma_f32_16x16x32_bf16 v[48:51], v[16:19], v[210:213], v[48:51]
	v_mfma_f32_16x16x32_bf16 v[44:47], v[40:43], v[210:213], v[44:47]
	v_mfma_f32_16x16x32_bf16 v[12:15], v[16:19], v[218:221], v[12:15]
	v_mfma_f32_16x16x32_bf16 v[16:19], v[36:39], v[214:217], 0
	v_mfma_f32_16x16x32_bf16 v[16:19], v[40:43], v[218:221], v[16:19]
	v_mfma_f32_16x16x32_bf16 v[20:23], v[148:151], v[164:167], 0
	v_mfma_f32_16x16x32_bf16 v[36:39], v[152:155], v[168:171], v[20:23]
	v_mfma_f32_16x16x32_bf16 v[20:23], v[156:159], v[164:167], 0
	v_mfma_f32_16x16x32_bf16 v[40:43], v[160:163], v[168:171], v[20:23]
	v_mfma_f32_16x16x32_bf16 v[20:23], v[148:151], v[198:201], 0
	v_mfma_f32_16x16x32_bf16 v[56:59], v[152:155], v[202:205], v[20:23]
	v_mfma_f32_16x16x32_bf16 v[20:23], v[156:159], v[198:201], 0
	v_mfma_f32_16x16x32_bf16 v[52:55], v[160:163], v[202:205], v[20:23]
	v_mfma_f32_16x16x32_bf16 v[20:23], v[148:151], v[206:209], 0
	v_mfma_f32_16x16x32_bf16 v[32:35], v[152:155], v[210:213], v[20:23]
	v_mfma_f32_16x16x32_bf16 v[20:23], v[156:159], v[206:209], 0
	v_mfma_f32_16x16x32_bf16 v[8:11], v[148:151], v[214:217], 0
	v_mfma_f32_16x16x32_bf16 v[4:7], v[156:159], v[214:217], 0
	v_mfma_f32_16x16x32_bf16 v[28:31], v[160:163], v[210:213], v[20:23]
	v_mfma_f32_16x16x32_bf16 v[8:11], v[152:155], v[218:221], v[8:11]
	v_mfma_f32_16x16x32_bf16 v[4:7], v[160:163], v[218:221], v[4:7]
	s_barrier
; #define PG8_STAGE(bufoff, gbase, voff) do { _Pragma("unroll") for (int _i = 0; _i < 2; ++_i) \
;         __builtin_amdgcn_global_load_lds((const unsigned*)((const char*)(gbase) + (voff)[_i]), (PG8_LAS unsigned*)(lds + (bufoff) + ldsw + _i * 8192), 16, 0, 0); } while (0)
; #define PG8_LDA(dst, b, h) do { _Pragma("unroll") for (int m = 0; m < 4; ++m) _Pragma("unroll") for (int k = 0; k < 2; ++k) dst[m][k] = *(const PG8_LAS bf16x8*)(lds + PG8_SA(b, h) + aoff + m * 2048 + k * 1024); } while (0)
; #define PG8_LDB(dst, b, h) do { _Pragma("unroll") for (int n = 0; n < 2; ++n) _Pragma("unroll") for (int k = 0; k < 2; ++k) dst[n][k] = *(const PG8_LAS bf16x8*)(lds + PG8_SB(b, h) + boff + n * 2048 + k * 1024); } while (0)
; #define PG8_MMA(ai, bj, At, Bt) do { __builtin_amdgcn_s_setprio(1); _Pragma("unroll") for (int m = 0; m < 4; ++m) _Pragma("unroll") for (int n = 0; n < 2; ++n) _Pragma("unroll") for (int k = 0; k < 2; ++k) \
;         acc[ai][bj][m][n] = __builtin_amdgcn_mfma_f32_16x16x32_bf16(Bt[n][k], At[m][k], acc[ai][bj][m][n], 0, 0, 0); __builtin_amdgcn_s_setprio(0); } while (0)
; #define PG8_WAIT_V(n) asm volatile("s_waitcnt vmcnt(" #n ")" ::: "memory")
; #define PG8_WAIT_L(n) asm volatile("s_waitcnt lgkmcnt(" #n ")" ::: "memory")
; #define PG8_BAR __builtin_amdgcn_s_barrier()
; #define PG8_SCHED __builtin_amdgcn_sched_barrier(0)
; template <class Epi, class Sched, bool ALIGN_EPI = false, bool SP2 = false>
; __device__ __forceinline__ void gemm_phase(PG8_LAS unsigned char* lds, const Gemm g, const Sched& S, const Epi& E, const int tid_) {
;     ...
;             PG8_LDB(B0, 1, 0); PG8_LDB(B1, 1, 1); PG8_SCHED; PG8_LDA(At, 1, 0); PG8_STAGE(PG8_SA(0, 1), a2 + hstep, voffA);
;             PG8_WAIT_V(8); PG8_WAIT_L(0); PG8_BAR; PG8_MMA(0, 0, At, B0); PG8_MMA(0, 1, At, B1); PG8_BAR; PG8_SCHED;
;             PG8_LDA(At, 1, 1); PG8_STAGE(PG8_SB(1, 0), b3, voffB); PG8_STAGE(PG8_SB(1, 1), b3 + hstepB, voffB); PG8_STAGE(PG8_SA(1, 0), a3, voffA);
;             PG8_WAIT_V(8); PG8_WAIT_L(0); PG8_BAR; PG8_MMA(1, 0, At, B0); PG8_MMA(1, 1, At, B1); PG8_BAR; PG8_SCHED;
	v_add_u32_e32 v72, s71, v197
	v_add_u32_e32 v160, s76, v197
	ds_read_b128 v[20:23], v72
	ds_read_b128 v[24:27], v72 offset:1024
	ds_read_b128 v[68:71], v72 offset:2048
	ds_read_b128 v[72:75], v72 offset:3072
	ds_read_b128 v[148:151], v160
	ds_read_b128 v[152:155], v160 offset:1024
	ds_read_b128 v[156:159], v160 offset:2048
	ds_read_b128 v[160:163], v160 offset:3072
	s_add_u32 s10, s10, s34
	s_addc_u32 s11, s11, s35
	s_mov_b32 m0, s69
	v_lshl_add_u64 v[232:233], s[10:11], 0, v[0:1]
	ds_read_b128 v[164:167], v238 offset:32768
	ds_read_b128 v[168:171], v238 offset:33792
	ds_read_b128 v[198:201], v238 offset:34816
	ds_read_b128 v[202:205], v238 offset:35840
	ds_read_b128 v[206:209], v238 offset:36864
	ds_read_b128 v[210:213], v238 offset:37888
	ds_read_b128 v[214:217], v238 offset:38912
	ds_read_b128 v[218:221], v238 offset:39936
	global_load_lds_dwordx4 v[232:233], off
	v_lshl_add_u64 v[232:233], s[10:11], 0, v[174:175]
	s_mov_b32 m0, s70
	s_nop 0
	global_load_lds_dwordx4 v[232:233], off
	s_waitcnt vmcnt(8)
	s_waitcnt lgkmcnt(0)
	s_barrier
	s_waitcnt lgkmcnt(0)
	v_mfma_f32_16x16x32_bf16 v[144:147], v[20:23], v[164:167], v[144:147]
	v_mfma_f32_16x16x32_bf16 v[140:143], v[68:71], v[164:167], v[140:143]
	v_mfma_f32_16x16x32_bf16 v[128:131], v[20:23], v[198:201], v[128:131]
	v_mfma_f32_16x16x32_bf16 v[124:127], v[68:71], v[198:201], v[124:127]
	v_mfma_f32_16x16x32_bf16 v[112:115], v[20:23], v[206:209], v[112:115]
	v_mfma_f32_16x16x32_bf16 v[108:111], v[68:71], v[206:209], v[108:111]
	v_mfma_f32_16x16x32_bf16 v[96:99], v[20:23], v[214:217], v[96:99]
	v_mfma_f32_16x16x32_bf16 v[92:95], v[68:71], v[214:217], v[92:95]
	v_mfma_f32_16x16x32_bf16 v[144:147], v[24:27], v[168:171], v[144:147]
	v_mfma_f32_16x16x32_bf16 v[140:143], v[72:75], v[168:171], v[140:143]
	v_mfma_f32_16x16x32_bf16 v[128:131], v[24:27], v[202:205], v[128:131]
	v_mfma_f32_16x16x32_bf16 v[124:127], v[72:75], v[202:205], v[124:127]
	v_mfma_f32_16x16x32_bf16 v[112:115], v[24:27], v[210:213], v[112:115]
	v_mfma_f32_16x16x32_bf16 v[108:111], v[72:75], v[210:213], v[108:111]
	v_mfma_f32_16x16x32_bf16 v[96:99], v[24:27], v[218:221], v[96:99]
	v_mfma_f32_16x16x32_bf16 v[92:95], v[72:75], v[218:221], v[92:95]
	v_mfma_f32_16x16x32_bf16 v[136:139], v[148:151], v[164:167], v[136:139]
	v_mfma_f32_16x16x32_bf16 v[132:135], v[156:159], v[164:167], v[132:135]
	v_mfma_f32_16x16x32_bf16 v[120:123], v[148:151], v[198:201], v[120:123]
	v_mfma_f32_16x16x32_bf16 v[116:119], v[156:159], v[198:201], v[116:119]
	v_mfma_f32_16x16x32_bf16 v[104:107], v[148:151], v[206:209], v[104:107]
	v_mfma_f32_16x16x32_bf16 v[100:103], v[156:159], v[206:209], v[100:103]
	v_mfma_f32_16x16x32_bf16 v[88:91], v[148:151], v[214:217], v[88:91]
	v_mfma_f32_16x16x32_bf16 v[84:87], v[156:159], v[214:217], v[84:87]
	v_mfma_f32_16x16x32_bf16 v[136:139], v[152:155], v[168:171], v[136:139]
	v_mfma_f32_16x16x32_bf16 v[132:135], v[160:163], v[168:171], v[132:135]
	v_mfma_f32_16x16x32_bf16 v[120:123], v[152:155], v[202:205], v[120:123]
	v_mfma_f32_16x16x32_bf16 v[116:119], v[160:163], v[202:205], v[116:119]
	v_mfma_f32_16x16x32_bf16 v[104:107], v[152:155], v[210:213], v[104:107]
	v_mfma_f32_16x16x32_bf16 v[100:103], v[160:163], v[210:213], v[100:103]
	v_mfma_f32_16x16x32_bf16 v[88:91], v[152:155], v[218:221], v[88:91]
	v_mfma_f32_16x16x32_bf16 v[84:87], v[160:163], v[218:221], v[84:87]
	s_barrier
	s_mov_b32 m0, s72
	v_lshl_add_u64 v[194:195], v[194:195], 0, s[96:97]
	ds_read_b128 v[164:167], v238 offset:49152
	ds_read_b128 v[168:171], v238 offset:50176
	ds_read_b128 v[198:201], v238 offset:51200
	ds_read_b128 v[202:205], v238 offset:52224
	ds_read_b128 v[206:209], v238 offset:53248
	ds_read_b128 v[210:213], v238 offset:54272
	ds_read_b128 v[214:217], v238 offset:55296
	ds_read_b128 v[218:221], v238 offset:56320
	global_load_lds_dwordx4 v[194:195], off
	v_lshl_add_u64 v[194:195], v[222:223], 0, s[96:97]
	s_mov_b32 m0, s73
	s_nop 0
	global_load_lds_dwordx4 v[194:195], off
	v_lshl_add_u64 v[194:195], v[224:225], 0, s[96:97]
	s_mov_b32 m0, s77
	s_nop 0
	global_load_lds_dwordx4 v[194:195], off
	v_lshl_add_u64 v[194:195], v[226:227], 0, s[96:97]
	s_mov_b32 m0, s80
	s_nop 0
	global_load_lds_dwordx4 v[194:195], off
	v_lshl_add_u64 v[194:195], v[228:229], 0, s[96:97]
	s_mov_b32 m0, s74
	s_nop 0
	global_load_lds_dwordx4 v[194:195], off
	v_lshl_add_u64 v[194:195], v[230:231], 0, s[96:97]
	s_mov_b32 m0, s75
	s_nop 0
	global_load_lds_dwordx4 v[194:195], off
	s_waitcnt vmcnt(8)
	s_waitcnt lgkmcnt(0)
	s_barrier
	s_waitcnt lgkmcnt(0)
	v_mfma_f32_16x16x32_bf16 v[80:83], v[20:23], v[164:167], v[80:83]
	v_mfma_f32_16x16x32_bf16 v[64:67], v[20:23], v[198:201], v[64:67]
	v_mfma_f32_16x16x32_bf16 v[48:51], v[20:23], v[206:209], v[48:51]
	v_mfma_f32_16x16x32_bf16 v[12:15], v[20:23], v[214:217], v[12:15]
	v_mfma_f32_16x16x32_bf16 v[80:83], v[24:27], v[168:171], v[80:83]
	v_mfma_f32_16x16x32_bf16 v[76:79], v[68:71], v[164:167], v[76:79]
	v_mfma_f32_16x16x32_bf16 v[64:67], v[24:27], v[202:205], v[64:67]
	v_mfma_f32_16x16x32_bf16 v[60:63], v[68:71], v[198:201], v[60:63]
	v_mfma_f32_16x16x32_bf16 v[48:51], v[24:27], v[210:213], v[48:51]
	v_mfma_f32_16x16x32_bf16 v[44:47], v[68:71], v[206:209], v[44:47]
	v_mfma_f32_16x16x32_bf16 v[24:27], v[24:27], v[218:221], v[12:15]
	v_mfma_f32_16x16x32_bf16 v[12:15], v[68:71], v[214:217], v[16:19]
	v_mfma_f32_16x16x32_bf16 v[76:79], v[72:75], v[168:171], v[76:79]
	v_mfma_f32_16x16x32_bf16 v[60:63], v[72:75], v[202:205], v[60:63]
	v_mfma_f32_16x16x32_bf16 v[44:47], v[72:75], v[210:213], v[44:47]
	v_mfma_f32_16x16x32_bf16 v[20:23], v[72:75], v[218:221], v[12:15]
	v_mfma_f32_16x16x32_bf16 v[12:15], v[148:151], v[164:167], v[36:39]
	v_mfma_f32_16x16x32_bf16 v[72:75], v[152:155], v[168:171], v[12:15]
	v_mfma_f32_16x16x32_bf16 v[12:15], v[156:159], v[164:167], v[40:43]
	v_mfma_f32_16x16x32_bf16 v[68:71], v[160:163], v[168:171], v[12:15]
	v_mfma_f32_16x16x32_bf16 v[12:15], v[148:151], v[198:201], v[56:59]
	v_mfma_f32_16x16x32_bf16 v[56:59], v[152:155], v[202:205], v[12:15]
	v_mfma_f32_16x16x32_bf16 v[12:15], v[156:159], v[198:201], v[52:55]
	v_mfma_f32_16x16x32_bf16 v[52:55], v[160:163], v[202:205], v[12:15]
	v_mfma_f32_16x16x32_bf16 v[12:15], v[148:151], v[206:209], v[32:35]
	v_mfma_f32_16x16x32_bf16 v[32:35], v[152:155], v[210:213], v[12:15]
	v_mfma_f32_16x16x32_bf16 v[12:15], v[156:159], v[206:209], v[28:31]
	v_mfma_f32_16x16x32_bf16 v[8:11], v[148:151], v[214:217], v[8:11]
	v_mfma_f32_16x16x32_bf16 v[4:7], v[156:159], v[214:217], v[4:7]
	v_mfma_f32_16x16x32_bf16 v[28:31], v[160:163], v[210:213], v[12:15]
	v_mfma_f32_16x16x32_bf16 v[8:11], v[152:155], v[218:221], v[8:11]
	v_mfma_f32_16x16x32_bf16 v[4:7], v[160:163], v[218:221], v[4:7]
	s_barrier
	s_add_u32 s8, s8, 0x100
	s_addc_u32 s9, s9, 0
	s_add_u32 s2, s2, 0x100
	s_addc_u32 s3, s3, 0
	s_cmp_ge_u32 s12, s81
	s_mov_b32 s10, s12
; #define PG8_STAGE(bufoff, gbase, voff) do { _Pragma("unroll") for (int _i = 0; _i < 2; ++_i) \
;         __builtin_amdgcn_global_load_lds((const unsigned*)((const char*)(gbase) + (voff)[_i]), (PG8_LAS unsigned*)(lds + (bufoff) + ldsw + _i * 8192), 16, 0, 0); } while (0)
; #define PG8_LDA(dst, b, h) do { _Pragma("unroll") for (int m = 0; m < 4; ++m) _Pragma("unroll") for (int k = 0; k < 2; ++k) dst[m][k] = *(const PG8_LAS bf16x8*)(lds + PG8_SA(b, h) + aoff + m * 2048 + k * 1024); } while (0)
; #define PG8_LDB(dst, b, h) do { _Pragma("unroll") for (int n = 0; n < 2; ++n) _Pragma("unroll") for (int k = 0; k < 2; ++k) dst[n][k] = *(const PG8_LAS bf16x8*)(lds + PG8_SB(b, h) + boff + n * 2048 + k * 1024); } while (0)
; #define PG8_MMA(ai, bj, At, Bt) do { __builtin_amdgcn_s_setprio(1); _Pragma("unroll") for (int m = 0; m < 4; ++m) _Pragma("unroll") for (int n = 0; n < 2; ++n) _Pragma("unroll") for (int k = 0; k < 2; ++k) \
;         acc[ai][bj][m][n] = __builtin_amdgcn_mfma_f32_16x16x32_bf16(Bt[n][k], At[m][k], acc[ai][bj][m][n], 0, 0, 0); __builtin_amdgcn_s_setprio(0); } while (0)
; #define PG8_WAIT_V(n) asm volatile("s_waitcnt vmcnt(" #n ")" ::: "memory")
; #define PG8_WAIT_L(n) asm volatile("s_waitcnt lgkmcnt(" #n ")" ::: "memory")
; #define PG8_BAR __builtin_amdgcn_s_barrier()
; template <class Epi, class Sched, bool ALIGN_EPI = false, bool SP2 = false>
; __device__ __forceinline__ void gemm_phase(PG8_LAS unsigned char* lds, const Gemm g, const Sched& S, const Epi& E, const int tid_) {
;     ...
;             const char* a1 = cA + (size_t)(t + 1) * kstep;
;             const char* a2 = last ? nA : cA + (size_t)(t + 2) * kstep; const char* b2 = last ? nB : cB + (size_t)(t + 2) * kstep;
;             const char* a3 = a2 + kstep; const char* b3 = b2 + kstep;
;             if (last && has_next) S.a_ready(nxt);
;             if constexpr (SP2) {
;             PG8_LDB(B0, 0, 0); PG8_LDB(B1, 0, 1); PG8_SCHED; PG8_LDA(At, 0, 0); PG8_STAGE(PG8_SA(1, 1), a1 + hstep, voffA);
;             PG8_WAIT_V(8); PG8_WAIT_L(0); PG8_BAR; PG8_MMA(0, 0, At, B0); PG8_MMA(0, 1, At, B1); PG8_BAR; PG8_SCHED;
;             PG8_LDA(At, 0, 1); PG8_STAGE(PG8_SB(0, 0), b2, voffB); PG8_STAGE(PG8_SB(0, 1), b2 + hstepB, voffB); PG8_STAGE(PG8_SA(0, 0), a2, voffA);
;             PG8_WAIT_V(8); PG8_WAIT_L(0); PG8_BAR; PG8_MMA(1, 0, At, B0); PG8_MMA(1, 1, At, B1); PG8_BAR; PG8_SCHED;
.LBB0_369:
	v_add_u32_e32 v40, s61, v197
	v_add_u32_e32 v160, s64, v197
	ds_read_b128 v[12:15], v40
	ds_read_b128 v[16:19], v40 offset:1024
	ds_read_b128 v[36:39], v40 offset:2048
	ds_read_b128 v[40:43], v40 offset:3072
	ds_read_b128 v[148:151], v160
	ds_read_b128 v[152:155], v160 offset:1024
	ds_read_b128 v[156:159], v160 offset:2048
	ds_read_b128 v[160:163], v160 offset:3072
	s_add_i32 s12, s10, 2
	s_add_u32 s13, s8, 0x80
	s_addc_u32 s11, s9, 0
	s_cmp_eq_u32 s82, s10
	s_cselect_b32 s10, s48, s13
	s_cselect_b32 s11, s49, s11
	s_cselect_b32 s53, s51, s3
	s_cselect_b32 s52, s50, s2
	v_lshl_add_u64 v[194:195], s[8:9], 0, v[190:191]
	s_add_i32 m0, s67, 0xc000
	ds_read_b128 v[164:167], v238
	ds_read_b128 v[168:171], v238 offset:1024
	ds_read_b128 v[198:201], v238 offset:2048
	ds_read_b128 v[202:205], v238 offset:3072
	ds_read_b128 v[206:209], v238 offset:4096
	ds_read_b128 v[210:213], v238 offset:5120
	ds_read_b128 v[214:217], v238 offset:6144
	ds_read_b128 v[218:221], v238 offset:7168
	global_load_lds_dwordx4 v[194:195], off
	v_lshl_add_u64 v[194:195], s[8:9], 0, v[192:193]
	s_add_i32 m0, s67, 0xe000
	s_nop 0
	global_load_lds_dwordx4 v[194:195], off
	s_waitcnt vmcnt(8)
	s_waitcnt lgkmcnt(0)
	s_barrier
	s_waitcnt lgkmcnt(0)
	v_mfma_f32_16x16x32_bf16 v[144:147], v[12:15], v[164:167], v[144:147]
	v_mfma_f32_16x16x32_bf16 v[140:143], v[36:39], v[164:167], v[140:143]
	v_mfma_f32_16x16x32_bf16 v[128:131], v[12:15], v[198:201], v[128:131]
	v_mfma_f32_16x16x32_bf16 v[124:127], v[36:39], v[198:201], v[124:127]
	v_mfma_f32_16x16x32_bf16 v[112:115], v[12:15], v[206:209], v[112:115]
	v_mfma_f32_16x16x32_bf16 v[108:111], v[36:39], v[206:209], v[108:111]
	v_mfma_f32_16x16x32_bf16 v[96:99], v[12:15], v[214:217], v[96:99]
	v_mfma_f32_16x16x32_bf16 v[92:95], v[36:39], v[214:217], v[92:95]
	v_mfma_f32_16x16x32_bf16 v[144:147], v[16:19], v[168:171], v[144:147]
	v_mfma_f32_16x16x32_bf16 v[140:143], v[40:43], v[168:171], v[140:143]
	v_mfma_f32_16x16x32_bf16 v[128:131], v[16:19], v[202:205], v[128:131]
	v_mfma_f32_16x16x32_bf16 v[124:127], v[40:43], v[202:205], v[124:127]
	v_mfma_f32_16x16x32_bf16 v[112:115], v[16:19], v[210:213], v[112:115]
	v_mfma_f32_16x16x32_bf16 v[108:111], v[40:43], v[210:213], v[108:111]
	v_mfma_f32_16x16x32_bf16 v[96:99], v[16:19], v[218:221], v[96:99]
	v_mfma_f32_16x16x32_bf16 v[92:95], v[40:43], v[218:221], v[92:95]
	v_mfma_f32_16x16x32_bf16 v[136:139], v[148:151], v[164:167], v[136:139]
	v_mfma_f32_16x16x32_bf16 v[132:135], v[156:159], v[164:167], v[132:135]
	v_mfma_f32_16x16x32_bf16 v[120:123], v[148:151], v[198:201], v[120:123]
	v_mfma_f32_16x16x32_bf16 v[116:119], v[156:159], v[198:201], v[116:119]
	v_mfma_f32_16x16x32_bf16 v[104:107], v[148:151], v[206:209], v[104:107]
	v_mfma_f32_16x16x32_bf16 v[100:103], v[156:159], v[206:209], v[100:103]
	v_mfma_f32_16x16x32_bf16 v[88:91], v[148:151], v[214:217], v[88:91]
	v_mfma_f32_16x16x32_bf16 v[84:87], v[156:159], v[214:217], v[84:87]
	v_mfma_f32_16x16x32_bf16 v[136:139], v[152:155], v[168:171], v[136:139]
	v_mfma_f32_16x16x32_bf16 v[132:135], v[160:163], v[168:171], v[132:135]
	v_mfma_f32_16x16x32_bf16 v[120:123], v[152:155], v[202:205], v[120:123]
	v_mfma_f32_16x16x32_bf16 v[116:119], v[160:163], v[202:205], v[116:119]
	v_mfma_f32_16x16x32_bf16 v[104:107], v[152:155], v[210:213], v[104:107]
	v_mfma_f32_16x16x32_bf16 v[100:103], v[160:163], v[210:213], v[100:103]
	v_mfma_f32_16x16x32_bf16 v[88:91], v[152:155], v[218:221], v[88:91]
	v_mfma_f32_16x16x32_bf16 v[84:87], v[160:163], v[218:221], v[84:87]
	s_barrier
	s_mov_b32 m0, s62
	v_lshl_add_u64 v[194:195], s[52:53], 0, v[172:173]
	v_lshl_add_u64 v[222:223], s[52:53], 0, v[176:177]
	s_add_u32 s52, s52, s38
	ds_read_b128 v[164:167], v238 offset:16384
	ds_read_b128 v[168:171], v238 offset:17408
	ds_read_b128 v[198:201], v238 offset:18432
	ds_read_b128 v[202:205], v238 offset:19456
	ds_read_b128 v[206:209], v238 offset:20480
	ds_read_b128 v[210:213], v238 offset:21504
	ds_read_b128 v[214:217], v238 offset:22528
	ds_read_b128 v[218:221], v238 offset:23552
	global_load_lds_dwordx4 v[194:195], off
	s_mov_b32 m0, s63
	s_addc_u32 s53, s53, s39
	global_load_lds_dwordx4 v[222:223], off
	v_lshl_add_u64 v[224:225], s[52:53], 0, v[172:173]
	s_mov_b32 m0, s65
	v_lshl_add_u64 v[226:227], s[52:53], 0, v[176:177]
	global_load_lds_dwordx4 v[224:225], off
	s_mov_b32 m0, s66
	v_lshl_add_u64 v[228:229], s[10:11], 0, v[0:1]
	global_load_lds_dwordx4 v[226:227], off
	s_mov_b32 m0, s67
	v_lshl_add_u64 v[230:231], s[10:11], 0, v[174:175]
	global_load_lds_dwordx4 v[228:229], off
	s_mov_b32 m0, s68
	s_nop 0
	global_load_lds_dwordx4 v[230:231], off
	s_waitcnt vmcnt(8)
	s_waitcnt lgkmcnt(0)
	s_barrier
; #define PG8_STAGE(bufoff, gbase, voff) do { _Pragma("unroll") for (int _i = 0; _i < 2; ++_i) \
;         __builtin_amdgcn_global_load_lds((const unsigned*)((const char*)(gbase) + (voff)[_i]), (PG8_LAS unsigned*)(lds + (bufoff) + ldsw + _i * 8192), 16, 0, 0); } while (0)
; #define PG8_LDA(dst, b, h) do { _Pragma("unroll") for (int m = 0; m < 4; ++m) _Pragma("unroll") for (int k = 0; k < 2; ++k) dst[m][k] = *(const PG8_LAS bf16x8*)(lds + PG8_SA(b, h) + aoff + m * 2048 + k * 1024); } while (0)
; #define PG8_LDB(dst, b, h) do { _Pragma("unroll") for (int n = 0; n < 2; ++n) _Pragma("unroll") for (int k = 0; k < 2; ++k) dst[n][k] = *(const PG8_LAS bf16x8*)(lds + PG8_SB(b, h) + boff + n * 2048 + k * 1024); } while (0)
; #define PG8_MMA(ai, bj, At, Bt) do { __builtin_amdgcn_s_setprio(1); _Pragma("unroll") for (int m = 0; m < 4; ++m) _Pragma("unroll") for (int n = 0; n < 2; ++n) _Pragma("unroll") for (int k = 0; k < 2; ++k) \
;         acc[ai][bj][m][n] = __builtin_amdgcn_mfma_f32_16x16x32_bf16(Bt[n][k], At[m][k], acc[ai][bj][m][n], 0, 0, 0); __builtin_amdgcn_s_setprio(0); } while (0)
; #define PG8_WAIT_V(n) asm volatile("s_waitcnt vmcnt(" #n ")" ::: "memory")
; #define PG8_WAIT_L(n) asm volatile("s_waitcnt lgkmcnt(" #n ")" ::: "memory")
; #define PG8_BAR __builtin_amdgcn_s_barrier()
; #define PG8_SCHED __builtin_amdgcn_sched_barrier(0)
; template <class Epi, class Sched, bool ALIGN_EPI = false, bool SP2 = false>
; __device__ __forceinline__ void gemm_phase(PG8_LAS unsigned char* lds, const Gemm g, const Sched& S, const Epi& E, const int tid_) {
;     ...
;             PG8_WAIT_V(8); PG8_WAIT_L(0); PG8_BAR; PG8_MMA(1, 0, At, B0); PG8_MMA(1, 1, At, B1); PG8_BAR; PG8_SCHED;
;             PG8_LDB(B0, 1, 0); PG8_LDB(B1, 1, 1); PG8_SCHED; PG8_LDA(At, 1, 0); PG8_STAGE(PG8_SA(0, 1), a2 + hstep, voffA);
;             PG8_WAIT_V(8); PG8_WAIT_L(0); PG8_BAR; PG8_MMA(0, 0, At, B0); PG8_MMA(0, 1, At, B1); PG8_BAR; PG8_SCHED;
	s_waitcnt lgkmcnt(0)
	v_mfma_f32_16x16x32_bf16 v[80:83], v[12:15], v[164:167], v[80:83]
	v_mfma_f32_16x16x32_bf16 v[76:79], v[36:39], v[164:167], v[76:79]
	v_mfma_f32_16x16x32_bf16 v[64:67], v[12:15], v[198:201], v[64:67]
	v_mfma_f32_16x16x32_bf16 v[60:63], v[36:39], v[198:201], v[60:63]
	v_mfma_f32_16x16x32_bf16 v[48:51], v[12:15], v[206:209], v[48:51]
	v_mfma_f32_16x16x32_bf16 v[44:47], v[36:39], v[206:209], v[44:47]
	v_mfma_f32_16x16x32_bf16 v[12:15], v[12:15], v[214:217], v[24:27]
	v_mfma_f32_16x16x32_bf16 v[80:83], v[16:19], v[168:171], v[80:83]
	v_mfma_f32_16x16x32_bf16 v[76:79], v[40:43], v[168:171], v[76:79]
	v_mfma_f32_16x16x32_bf16 v[64:67], v[16:19], v[202:205], v[64:67]
	v_mfma_f32_16x16x32_bf16 v[60:63], v[40:43], v[202:205], v[60:63]
	v_mfma_f32_16x16x32_bf16 v[48:51], v[16:19], v[210:213], v[48:51]
	v_mfma_f32_16x16x32_bf16 v[44:47], v[40:43], v[210:213], v[44:47]
	v_mfma_f32_16x16x32_bf16 v[12:15], v[16:19], v[218:221], v[12:15]
	v_mfma_f32_16x16x32_bf16 v[16:19], v[36:39], v[214:217], v[20:23]
	v_mfma_f32_16x16x32_bf16 v[16:19], v[40:43], v[218:221], v[16:19]
	v_mfma_f32_16x16x32_bf16 v[20:23], v[148:151], v[164:167], v[72:75]
	v_mfma_f32_16x16x32_bf16 v[36:39], v[152:155], v[168:171], v[20:23]
	v_mfma_f32_16x16x32_bf16 v[20:23], v[156:159], v[164:167], v[68:71]
	v_mfma_f32_16x16x32_bf16 v[40:43], v[160:163], v[168:171], v[20:23]
	v_mfma_f32_16x16x32_bf16 v[20:23], v[148:151], v[198:201], v[56:59]
	v_mfma_f32_16x16x32_bf16 v[56:59], v[152:155], v[202:205], v[20:23]
	v_mfma_f32_16x16x32_bf16 v[20:23], v[156:159], v[198:201], v[52:55]
	v_mfma_f32_16x16x32_bf16 v[52:55], v[160:163], v[202:205], v[20:23]
	v_mfma_f32_16x16x32_bf16 v[20:23], v[148:151], v[206:209], v[32:35]
	v_mfma_f32_16x16x32_bf16 v[32:35], v[152:155], v[210:213], v[20:23]
	v_mfma_f32_16x16x32_bf16 v[20:23], v[156:159], v[206:209], v[28:31]
	v_mfma_f32_16x16x32_bf16 v[8:11], v[148:151], v[214:217], v[8:11]
	v_mfma_f32_16x16x32_bf16 v[4:7], v[156:159], v[214:217], v[4:7]
	v_mfma_f32_16x16x32_bf16 v[28:31], v[160:163], v[210:213], v[20:23]
	v_mfma_f32_16x16x32_bf16 v[8:11], v[152:155], v[218:221], v[8:11]
	v_mfma_f32_16x16x32_bf16 v[4:7], v[160:163], v[218:221], v[4:7]
	s_barrier
	v_add_u32_e32 v72, s71, v197
	v_add_u32_e32 v160, s76, v197
	ds_read_b128 v[20:23], v72
	ds_read_b128 v[24:27], v72 offset:1024
	ds_read_b128 v[68:71], v72 offset:2048
	ds_read_b128 v[72:75], v72 offset:3072
	ds_read_b128 v[148:151], v160
	ds_read_b128 v[152:155], v160 offset:1024
	ds_read_b128 v[156:159], v160 offset:2048
	ds_read_b128 v[160:163], v160 offset:3072
	s_add_u32 s10, s10, s34
	s_addc_u32 s11, s11, s35
	s_mov_b32 m0, s69
	v_lshl_add_u64 v[232:233], s[10:11], 0, v[0:1]
	ds_read_b128 v[164:167], v238 offset:32768
	ds_read_b128 v[168:171], v238 offset:33792
	ds_read_b128 v[198:201], v238 offset:34816
	ds_read_b128 v[202:205], v238 offset:35840
	ds_read_b128 v[206:209], v238 offset:36864
	ds_read_b128 v[210:213], v238 offset:37888
	ds_read_b128 v[214:217], v238 offset:38912
	ds_read_b128 v[218:221], v238 offset:39936
	global_load_lds_dwordx4 v[232:233], off
	v_lshl_add_u64 v[232:233], s[10:11], 0, v[174:175]
	s_mov_b32 m0, s70
	s_nop 0
	global_load_lds_dwordx4 v[232:233], off
	s_waitcnt vmcnt(8)
	s_waitcnt lgkmcnt(0)
	s_barrier
	s_waitcnt lgkmcnt(0)
	v_mfma_f32_16x16x32_bf16 v[144:147], v[20:23], v[164:167], v[144:147]
	v_mfma_f32_16x16x32_bf16 v[140:143], v[68:71], v[164:167], v[140:143]
	v_mfma_f32_16x16x32_bf16 v[128:131], v[20:23], v[198:201], v[128:131]
	v_mfma_f32_16x16x32_bf16 v[124:127], v[68:71], v[198:201], v[124:127]
	v_mfma_f32_16x16x32_bf16 v[112:115], v[20:23], v[206:209], v[112:115]
	v_mfma_f32_16x16x32_bf16 v[108:111], v[68:71], v[206:209], v[108:111]
	v_mfma_f32_16x16x32_bf16 v[96:99], v[20:23], v[214:217], v[96:99]
	v_mfma_f32_16x16x32_bf16 v[92:95], v[68:71], v[214:217], v[92:95]
	v_mfma_f32_16x16x32_bf16 v[144:147], v[24:27], v[168:171], v[144:147]
	v_mfma_f32_16x16x32_bf16 v[140:143], v[72:75], v[168:171], v[140:143]
	v_mfma_f32_16x16x32_bf16 v[128:131], v[24:27], v[202:205], v[128:131]
	v_mfma_f32_16x16x32_bf16 v[124:127], v[72:75], v[202:205], v[124:127]
	v_mfma_f32_16x16x32_bf16 v[112:115], v[24:27], v[210:213], v[112:115]
	v_mfma_f32_16x16x32_bf16 v[108:111], v[72:75], v[210:213], v[108:111]
	v_mfma_f32_16x16x32_bf16 v[96:99], v[24:27], v[218:221], v[96:99]
	v_mfma_f32_16x16x32_bf16 v[92:95], v[72:75], v[218:221], v[92:95]
	v_mfma_f32_16x16x32_bf16 v[136:139], v[148:151], v[164:167], v[136:139]
	v_mfma_f32_16x16x32_bf16 v[132:135], v[156:159], v[164:167], v[132:135]
	v_mfma_f32_16x16x32_bf16 v[120:123], v[148:151], v[198:201], v[120:123]
	v_mfma_f32_16x16x32_bf16 v[116:119], v[156:159], v[198:201], v[116:119]
	v_mfma_f32_16x16x32_bf16 v[104:107], v[148:151], v[206:209], v[104:107]
	v_mfma_f32_16x16x32_bf16 v[100:103], v[156:159], v[206:209], v[100:103]
	v_mfma_f32_16x16x32_bf16 v[88:91], v[148:151], v[214:217], v[88:91]
	v_mfma_f32_16x16x32_bf16 v[84:87], v[156:159], v[214:217], v[84:87]
	v_mfma_f32_16x16x32_bf16 v[136:139], v[152:155], v[168:171], v[136:139]
	v_mfma_f32_16x16x32_bf16 v[132:135], v[160:163], v[168:171], v[132:135]
	v_mfma_f32_16x16x32_bf16 v[120:123], v[152:155], v[202:205], v[120:123]
	v_mfma_f32_16x16x32_bf16 v[116:119], v[160:163], v[202:205], v[116:119]
	v_mfma_f32_16x16x32_bf16 v[104:107], v[152:155], v[210:213], v[104:107]
	v_mfma_f32_16x16x32_bf16 v[100:103], v[160:163], v[210:213], v[100:103]
	v_mfma_f32_16x16x32_bf16 v[88:91], v[152:155], v[218:221], v[88:91]
	v_mfma_f32_16x16x32_bf16 v[84:87], v[160:163], v[218:221], v[84:87]
	s_barrier
; #define PG8_STAGE(bufoff, gbase, voff) do { _Pragma("unroll") for (int _i = 0; _i < 2; ++_i) \
;         __builtin_amdgcn_global_load_lds((const unsigned*)((const char*)(gbase) + (voff)[_i]), (PG8_LAS unsigned*)(lds + (bufoff) + ldsw + _i * 8192), 16, 0, 0); } while (0)
; #define PG8_LDA(dst, b, h) do { _Pragma("unroll") for (int m = 0; m < 4; ++m) _Pragma("unroll") for (int k = 0; k < 2; ++k) dst[m][k] = *(const PG8_LAS bf16x8*)(lds + PG8_SA(b, h) + aoff + m * 2048 + k * 1024); } while (0)
; #define PG8_MMA(ai, bj, At, Bt) do { __builtin_amdgcn_s_setprio(1); _Pragma("unroll") for (int m = 0; m < 4; ++m) _Pragma("unroll") for (int n = 0; n < 2; ++n) _Pragma("unroll") for (int k = 0; k < 2; ++k) \
;         acc[ai][bj][m][n] = __builtin_amdgcn_mfma_f32_16x16x32_bf16(Bt[n][k], At[m][k], acc[ai][bj][m][n], 0, 0, 0); __builtin_amdgcn_s_setprio(0); } while (0)
; #define PG8_WAIT_V(n) asm volatile("s_waitcnt vmcnt(" #n ")" ::: "memory")
; #define PG8_WAIT_L(n) asm volatile("s_waitcnt lgkmcnt(" #n ")" ::: "memory")
; #define PG8_BAR __builtin_amdgcn_s_barrier()
; #define PG8_SCHED __builtin_amdgcn_sched_barrier(0)
; template <class Epi, class Sched, bool ALIGN_EPI = false, bool SP2 = false>
; __device__ __forceinline__ void gemm_phase(PG8_LAS unsigned char* lds, const Gemm g, const Sched& S, const Epi& E, const int tid_) {
;     ...
;             PG8_LDA(At, 1, 1); PG8_STAGE(PG8_SB(1, 0), b3, voffB); PG8_STAGE(PG8_SB(1, 1), b3 + hstepB, voffB); PG8_STAGE(PG8_SA(1, 0), a3, voffA);
;             PG8_WAIT_V(8); PG8_WAIT_L(0); PG8_BAR; PG8_MMA(1, 0, At, B0); PG8_MMA(1, 1, At, B1); PG8_BAR; PG8_SCHED;
	s_mov_b32 m0, s72
	v_lshl_add_u64 v[194:195], v[194:195], 0, s[96:97]
	ds_read_b128 v[164:167], v238 offset:49152
	ds_read_b128 v[168:171], v238 offset:50176
	ds_read_b128 v[198:201], v238 offset:51200
	ds_read_b128 v[202:205], v238 offset:52224
	ds_read_b128 v[206:209], v238 offset:53248
	ds_read_b128 v[210:213], v238 offset:54272
	ds_read_b128 v[214:217], v238 offset:55296
	ds_read_b128 v[218:221], v238 offset:56320
	global_load_lds_dwordx4 v[194:195], off
	v_lshl_add_u64 v[194:195], v[222:223], 0, s[96:97]
	s_mov_b32 m0, s73
	s_nop 0
	global_load_lds_dwordx4 v[194:195], off
	v_lshl_add_u64 v[194:195], v[224:225], 0, s[96:97]
	s_mov_b32 m0, s77
	s_nop 0
	global_load_lds_dwordx4 v[194:195], off
	v_lshl_add_u64 v[194:195], v[226:227], 0, s[96:97]
	s_mov_b32 m0, s80
	s_nop 0
	global_load_lds_dwordx4 v[194:195], off
	v_lshl_add_u64 v[194:195], v[228:229], 0, s[96:97]
	s_mov_b32 m0, s74
	s_nop 0
	global_load_lds_dwordx4 v[194:195], off
	v_lshl_add_u64 v[194:195], v[230:231], 0, s[96:97]
	s_mov_b32 m0, s75
	s_nop 0
	global_load_lds_dwordx4 v[194:195], off
	s_waitcnt vmcnt(8)
	s_waitcnt lgkmcnt(0)
	s_barrier
	s_waitcnt lgkmcnt(0)
	v_mfma_f32_16x16x32_bf16 v[80:83], v[20:23], v[164:167], v[80:83]
	v_mfma_f32_16x16x32_bf16 v[64:67], v[20:23], v[198:201], v[64:67]
	v_mfma_f32_16x16x32_bf16 v[48:51], v[20:23], v[206:209], v[48:51]
	v_mfma_f32_16x16x32_bf16 v[12:15], v[20:23], v[214:217], v[12:15]
	v_mfma_f32_16x16x32_bf16 v[80:83], v[24:27], v[168:171], v[80:83]
	v_mfma_f32_16x16x32_bf16 v[76:79], v[68:71], v[164:167], v[76:79]
	v_mfma_f32_16x16x32_bf16 v[64:67], v[24:27], v[202:205], v[64:67]
	v_mfma_f32_16x16x32_bf16 v[60:63], v[68:71], v[198:201], v[60:63]
	v_mfma_f32_16x16x32_bf16 v[48:51], v[24:27], v[210:213], v[48:51]
	v_mfma_f32_16x16x32_bf16 v[44:47], v[68:71], v[206:209], v[44:47]
	v_mfma_f32_16x16x32_bf16 v[24:27], v[24:27], v[218:221], v[12:15]
	v_mfma_f32_16x16x32_bf16 v[12:15], v[68:71], v[214:217], v[16:19]
	v_mfma_f32_16x16x32_bf16 v[76:79], v[72:75], v[168:171], v[76:79]
	v_mfma_f32_16x16x32_bf16 v[60:63], v[72:75], v[202:205], v[60:63]
	v_mfma_f32_16x16x32_bf16 v[44:47], v[72:75], v[210:213], v[44:47]
	v_mfma_f32_16x16x32_bf16 v[20:23], v[72:75], v[218:221], v[12:15]
	v_mfma_f32_16x16x32_bf16 v[12:15], v[148:151], v[164:167], v[36:39]
	v_mfma_f32_16x16x32_bf16 v[72:75], v[152:155], v[168:171], v[12:15]
	v_mfma_f32_16x16x32_bf16 v[12:15], v[156:159], v[164:167], v[40:43]
	v_mfma_f32_16x16x32_bf16 v[68:71], v[160:163], v[168:171], v[12:15]
	v_mfma_f32_16x16x32_bf16 v[12:15], v[148:151], v[198:201], v[56:59]
	v_mfma_f32_16x16x32_bf16 v[56:59], v[152:155], v[202:205], v[12:15]
	v_mfma_f32_16x16x32_bf16 v[12:15], v[156:159], v[198:201], v[52:55]
	v_mfma_f32_16x16x32_bf16 v[52:55], v[160:163], v[202:205], v[12:15]
	v_mfma_f32_16x16x32_bf16 v[12:15], v[148:151], v[206:209], v[32:35]
	v_mfma_f32_16x16x32_bf16 v[32:35], v[152:155], v[210:213], v[12:15]
	v_mfma_f32_16x16x32_bf16 v[12:15], v[156:159], v[206:209], v[28:31]
	v_mfma_f32_16x16x32_bf16 v[8:11], v[148:151], v[214:217], v[8:11]
	v_mfma_f32_16x16x32_bf16 v[4:7], v[156:159], v[214:217], v[4:7]
	v_mfma_f32_16x16x32_bf16 v[28:31], v[160:163], v[210:213], v[12:15]
	v_mfma_f32_16x16x32_bf16 v[8:11], v[152:155], v[218:221], v[8:11]
	v_mfma_f32_16x16x32_bf16 v[4:7], v[160:163], v[218:221], v[4:7]
	s_barrier
	s_add_u32 s8, s8, 0x100
	s_addc_u32 s9, s9, 0
	s_add_u32 s2, s2, 0x100
	s_addc_u32 s3, s3, 0
	s_cmp_ge_u32 s12, s81
	s_mov_b32 s10, s12
	s_cbranch_scc0 .LBB0_369
	s_and_b64 vcc, exec, s[84:85]
	s_cbranch_vccz .LBB0_372
	s_barrier

; #define PG8_STAGE(bufoff, gbase, voff) do { _Pragma("unroll") for (int _i = 0; _i < 2; ++_i) \
;         __builtin_amdgcn_global_load_lds((const unsigned*)((const char*)(gbase) + (voff)[_i]), (PG8_LAS unsigned*)(lds + (bufoff) + ldsw + _i * 8192), 16, 0, 0); } while (0)
; #define PG8_LDA(dst, b, h) do { _Pragma("unroll") for (int m = 0; m < 4; ++m) _Pragma("unroll") for (int k = 0; k < 2; ++k) dst[m][k] = *(const PG8_LAS bf16x8*)(lds + PG8_SA(b, h) + aoff + m * 2048 + k * 1024); } while (0)
; #define PG8_LDB(dst, b, h) do { _Pragma("unroll") for (int n = 0; n < 2; ++n) _Pragma("unroll") for (int k = 0; k < 2; ++k) dst[n][k] = *(const PG8_LAS bf16x8*)(lds + PG8_SB(b, h) + boff + n * 2048 + k * 1024); } while (0)
; #define PG8_MMA(ai, bj, At, Bt) do { __builtin_amdgcn_s_setprio(1); _Pragma("unroll") for (int m = 0; m < 4; ++m) _Pragma("unroll") for (int n = 0; n < 2; ++n) _Pragma("unroll") for (int k = 0; k < 2; ++k) \
;         acc[ai][bj][m][n] = __builtin_amdgcn_mfma_f32_16x16x32_bf16(Bt[n][k], At[m][k], acc[ai][bj][m][n], 0, 0, 0); __builtin_amdgcn_s_setprio(0); } while (0)
; #define PG8_WAIT_V(n) asm volatile("s_waitcnt vmcnt(" #n ")" ::: "memory")
; #define PG8_WAIT_L(n) asm volatile("s_waitcnt lgkmcnt(" #n ")" ::: "memory")
; #define PG8_BAR __builtin_amdgcn_s_barrier()
; #define PG8_SCHED __builtin_amdgcn_sched_barrier(0)
; template <class Epi, class Sched, bool ALIGN_EPI = false, bool SP2 = false>
; __device__ __forceinline__ void gemm_phase(PG8_LAS unsigned char* lds, const Gemm g, const Sched& S, const Epi& E, const int tid_) {
;     ...
;             PG8_LDB(B0, 0, 0); PG8_LDB(B1, 0, 1); PG8_SCHED; PG8_LDA(At, 0, 0); PG8_STAGE(PG8_SA(1, 1), a1 + hstep, voffA);
;             PG8_WAIT_V(8); PG8_WAIT_L(0); PG8_BAR; PG8_MMA(0, 0, At, B0); PG8_MMA(0, 1, At, B1); PG8_BAR; PG8_SCHED;
;             PG8_LDA(At, 0, 1); PG8_STAGE(PG8_SB(0, 0), b2, voffB); PG8_STAGE(PG8_SB(0, 1), b2 + hstepB, voffB); PG8_STAGE(PG8_SA(0, 0), a2, voffA);
;             PG8_WAIT_V(8); PG8_WAIT_L(0); PG8_BAR; PG8_MMA(1, 0, At, B0); PG8_MMA(1, 1, At, B1); PG8_BAR; PG8_SCHED;
.Lpeel2_rs0:
	s_waitcnt lgkmcnt(0)
	s_barrier
	s_waitcnt lgkmcnt(0)
	v_mfma_f32_16x16x32_bf16 v[144:147], v[36:39], v[164:167], 0
	v_mfma_f32_16x16x32_bf16 v[140:143], v[48:51], v[164:167], 0
	v_mfma_f32_16x16x32_bf16 v[128:131], v[36:39], v[172:175], 0
	v_mfma_f32_16x16x32_bf16 v[124:127], v[48:51], v[172:175], 0
	v_mfma_f32_16x16x32_bf16 v[112:115], v[36:39], v[196:199], 0
	v_mfma_f32_16x16x32_bf16 v[108:111], v[48:51], v[196:199], 0
	v_mfma_f32_16x16x32_bf16 v[96:99], v[36:39], v[204:207], 0
	v_mfma_f32_16x16x32_bf16 v[92:95], v[48:51], v[204:207], 0
	v_mfma_f32_16x16x32_bf16 v[144:147], v[40:43], v[168:171], v[144:147]
	v_mfma_f32_16x16x32_bf16 v[140:143], v[56:59], v[168:171], v[140:143]
	v_mfma_f32_16x16x32_bf16 v[128:131], v[40:43], v[176:179], v[128:131]
	v_mfma_f32_16x16x32_bf16 v[124:127], v[56:59], v[176:179], v[124:127]
	v_mfma_f32_16x16x32_bf16 v[112:115], v[40:43], v[200:203], v[112:115]
	v_mfma_f32_16x16x32_bf16 v[108:111], v[56:59], v[200:203], v[108:111]
	v_mfma_f32_16x16x32_bf16 v[96:99], v[40:43], v[208:211], v[96:99]
	v_mfma_f32_16x16x32_bf16 v[92:95], v[56:59], v[208:211], v[92:95]
	v_mfma_f32_16x16x32_bf16 v[136:139], v[148:151], v[164:167], 0
	v_mfma_f32_16x16x32_bf16 v[132:135], v[156:159], v[164:167], 0
	v_mfma_f32_16x16x32_bf16 v[120:123], v[148:151], v[172:175], 0
	v_mfma_f32_16x16x32_bf16 v[116:119], v[156:159], v[172:175], 0
	v_mfma_f32_16x16x32_bf16 v[104:107], v[148:151], v[196:199], 0
	v_mfma_f32_16x16x32_bf16 v[100:103], v[156:159], v[196:199], 0
	v_mfma_f32_16x16x32_bf16 v[88:91], v[148:151], v[204:207], 0
	v_mfma_f32_16x16x32_bf16 v[84:87], v[156:159], v[204:207], 0
	v_mfma_f32_16x16x32_bf16 v[136:139], v[152:155], v[168:171], v[136:139]
	v_mfma_f32_16x16x32_bf16 v[132:135], v[160:163], v[168:171], v[132:135]
	v_mfma_f32_16x16x32_bf16 v[120:123], v[152:155], v[176:179], v[120:123]
	v_mfma_f32_16x16x32_bf16 v[116:119], v[160:163], v[176:179], v[116:119]
	v_mfma_f32_16x16x32_bf16 v[104:107], v[152:155], v[200:203], v[104:107]
	v_mfma_f32_16x16x32_bf16 v[100:103], v[160:163], v[200:203], v[100:103]
	v_mfma_f32_16x16x32_bf16 v[88:91], v[152:155], v[208:211], v[88:91]
	v_mfma_f32_16x16x32_bf16 v[84:87], v[160:163], v[208:211], v[84:87]
	s_barrier
	s_mov_b32 m0, s54
	v_lshl_add_u64 v[212:213], s[48:49], 0, v[2:3]
	v_lshl_add_u64 v[218:219], s[48:49], 0, v[190:191]
	s_add_u32 s48, s48, s52
	ds_read_b128 v[164:167], v216 offset:16384
	ds_read_b128 v[168:171], v216 offset:17408
	ds_read_b128 v[172:175], v216 offset:18432
	ds_read_b128 v[176:179], v216 offset:19456
	ds_read_b128 v[196:199], v216 offset:20480
	ds_read_b128 v[200:203], v216 offset:21504
	ds_read_b128 v[204:207], v216 offset:22528
	ds_read_b128 v[208:211], v216 offset:23552
	global_load_lds_dwordx4 v[212:213], off
	s_mov_b32 m0, s55
	s_addc_u32 s49, s49, 0
	global_load_lds_dwordx4 v[218:219], off
	v_lshl_add_u64 v[220:221], s[48:49], 0, v[2:3]
	s_mov_b32 m0, s57
	v_lshl_add_u64 v[222:223], s[48:49], 0, v[190:191]
	global_load_lds_dwordx4 v[220:221], off
	s_mov_b32 m0, s58
	v_lshl_add_u64 v[224:225], s[14:15], 0, v[0:1]
	global_load_lds_dwordx4 v[222:223], off
	s_mov_b32 m0, s59
	v_lshl_add_u64 v[226:227], s[14:15], 0, v[188:189]
	global_load_lds_dwordx4 v[224:225], off
	s_mov_b32 m0, s60
	s_nop 0
	global_load_lds_dwordx4 v[226:227], off
	s_cmp_lg_u32 s71, 1
	s_cbranch_scc1 .Lpeel2_rs1
	s_waitcnt vmcnt(8)
.Lpeel2_rs1:
	s_waitcnt lgkmcnt(0)
	s_barrier
	s_waitcnt lgkmcnt(0)
	v_mfma_f32_16x16x32_bf16 v[80:83], v[36:39], v[164:167], 0
	v_mfma_f32_16x16x32_bf16 v[76:79], v[48:51], v[164:167], 0
	v_mfma_f32_16x16x32_bf16 v[64:67], v[36:39], v[172:175], 0
	v_mfma_f32_16x16x32_bf16 v[60:63], v[48:51], v[172:175], 0
	v_mfma_f32_16x16x32_bf16 v[32:35], v[36:39], v[196:199], 0
	v_mfma_f32_16x16x32_bf16 v[28:31], v[48:51], v[196:199], 0
	v_mfma_f32_16x16x32_bf16 v[16:19], v[36:39], v[204:207], 0
	v_mfma_f32_16x16x32_bf16 v[12:15], v[48:51], v[204:207], 0
	v_mfma_f32_16x16x32_bf16 v[80:83], v[40:43], v[168:171], v[80:83]
	v_mfma_f32_16x16x32_bf16 v[76:79], v[56:59], v[168:171], v[76:79]
	v_mfma_f32_16x16x32_bf16 v[64:67], v[40:43], v[176:179], v[64:67]
	v_mfma_f32_16x16x32_bf16 v[60:63], v[56:59], v[176:179], v[60:63]
	v_mfma_f32_16x16x32_bf16 v[32:35], v[40:43], v[200:203], v[32:35]
	v_mfma_f32_16x16x32_bf16 v[28:31], v[56:59], v[200:203], v[28:31]
	v_mfma_f32_16x16x32_bf16 v[16:19], v[40:43], v[208:211], v[16:19]
	v_mfma_f32_16x16x32_bf16 v[12:15], v[56:59], v[208:211], v[12:15]
	v_mfma_f32_16x16x32_bf16 v[44:47], v[156:159], v[172:175], 0
	v_mfma_f32_16x16x32_bf16 v[24:27], v[148:151], v[196:199], 0
	v_mfma_f32_16x16x32_bf16 v[20:23], v[156:159], v[196:199], 0
	v_mfma_f32_16x16x32_bf16 v[8:11], v[148:151], v[204:207], 0
	v_mfma_f32_16x16x32_bf16 v[4:7], v[156:159], v[204:207], 0
	v_mfma_f32_16x16x32_bf16 v[36:39], v[148:151], v[164:167], 0
	v_mfma_f32_16x16x32_bf16 v[40:43], v[156:159], v[164:167], 0
	v_mfma_f32_16x16x32_bf16 v[48:51], v[148:151], v[172:175], 0
	v_mfma_f32_16x16x32_bf16 v[44:47], v[160:163], v[176:179], v[44:47]
	v_mfma_f32_16x16x32_bf16 v[24:27], v[152:155], v[200:203], v[24:27]
	v_mfma_f32_16x16x32_bf16 v[20:23], v[160:163], v[200:203], v[20:23]
	v_mfma_f32_16x16x32_bf16 v[8:11], v[152:155], v[208:211], v[8:11]
	v_mfma_f32_16x16x32_bf16 v[4:7], v[160:163], v[208:211], v[4:7]
	v_mfma_f32_16x16x32_bf16 v[36:39], v[152:155], v[168:171], v[36:39]
	v_mfma_f32_16x16x32_bf16 v[40:43], v[160:163], v[168:171], v[40:43]
	v_mfma_f32_16x16x32_bf16 v[48:51], v[152:155], v[176:179], v[48:51]
	s_barrier
; #define PG8_STAGE(bufoff, gbase, voff) do { _Pragma("unroll") for (int _i = 0; _i < 2; ++_i) \
;         __builtin_amdgcn_global_load_lds((const unsigned*)((const char*)(gbase) + (voff)[_i]), (PG8_LAS unsigned*)(lds + (bufoff) + ldsw + _i * 8192), 16, 0, 0); } while (0)
; #define PG8_LDA(dst, b, h) do { _Pragma("unroll") for (int m = 0; m < 4; ++m) _Pragma("unroll") for (int k = 0; k < 2; ++k) dst[m][k] = *(const PG8_LAS bf16x8*)(lds + PG8_SA(b, h) + aoff + m * 2048 + k * 1024); } while (0)
; #define PG8_LDB(dst, b, h) do { _Pragma("unroll") for (int n = 0; n < 2; ++n) _Pragma("unroll") for (int k = 0; k < 2; ++k) dst[n][k] = *(const PG8_LAS bf16x8*)(lds + PG8_SB(b, h) + boff + n * 2048 + k * 1024); } while (0)
; #define PG8_MMA(ai, bj, At, Bt) do { __builtin_amdgcn_s_setprio(1); _Pragma("unroll") for (int m = 0; m < 4; ++m) _Pragma("unroll") for (int n = 0; n < 2; ++n) _Pragma("unroll") for (int k = 0; k < 2; ++k) \
;         acc[ai][bj][m][n] = __builtin_amdgcn_mfma_f32_16x16x32_bf16(Bt[n][k], At[m][k], acc[ai][bj][m][n], 0, 0, 0); __builtin_amdgcn_s_setprio(0); } while (0)
; #define PG8_WAIT_V(n) asm volatile("s_waitcnt vmcnt(" #n ")" ::: "memory")
; #define PG8_WAIT_L(n) asm volatile("s_waitcnt lgkmcnt(" #n ")" ::: "memory")
; #define PG8_BAR __builtin_amdgcn_s_barrier()
; #define PG8_SCHED __builtin_amdgcn_sched_barrier(0)
; template <class Epi, class Sched, bool ALIGN_EPI = false, bool SP2 = false>
; __device__ __forceinline__ void gemm_phase(PG8_LAS unsigned char* lds, const Gemm g, const Sched& S, const Epi& E, const int tid_) {
;     ...
;             PG8_LDB(B0, 1, 0); PG8_LDB(B1, 1, 1); PG8_SCHED; PG8_LDA(At, 1, 0); PG8_STAGE(PG8_SA(0, 1), a2 + hstep, voffA);
;             PG8_WAIT_V(8); PG8_WAIT_L(0); PG8_BAR; PG8_MMA(0, 0, At, B0); PG8_MMA(0, 1, At, B1); PG8_BAR; PG8_SCHED;
;             PG8_LDA(At, 1, 1); PG8_STAGE(PG8_SB(1, 0), b3, voffB); PG8_STAGE(PG8_SB(1, 1), b3 + hstepB, voffB); PG8_STAGE(PG8_SA(1, 0), a3, voffA);
;             PG8_WAIT_V(8); PG8_WAIT_L(0); PG8_BAR; PG8_MMA(1, 0, At, B0); PG8_MMA(1, 1, At, B1); PG8_BAR; PG8_SCHED;
	v_add_u32_e32 v72, s63, v214
	v_add_u32_e32 v160, s68, v214
	ds_read_b128 v[52:55], v72
	ds_read_b128 v[56:59], v72 offset:1024
	ds_read_b128 v[68:71], v72 offset:2048
	ds_read_b128 v[72:75], v72 offset:3072
	ds_read_b128 v[148:151], v160
	ds_read_b128 v[152:155], v160 offset:1024
	ds_read_b128 v[156:159], v160 offset:2048
	ds_read_b128 v[160:163], v160 offset:3072
	s_add_u32 s14, s14, s24
	s_addc_u32 s15, s15, 0
	s_mov_b32 m0, s61
	v_lshl_add_u64 v[228:229], s[14:15], 0, v[0:1]
	ds_read_b128 v[164:167], v216 offset:32768
	ds_read_b128 v[168:171], v216 offset:33792
	ds_read_b128 v[172:175], v216 offset:34816
	ds_read_b128 v[176:179], v216 offset:35840
	ds_read_b128 v[196:199], v216 offset:36864
	ds_read_b128 v[200:203], v216 offset:37888
	ds_read_b128 v[204:207], v216 offset:38912
	ds_read_b128 v[208:211], v216 offset:39936
	global_load_lds_dwordx4 v[228:229], off
	v_lshl_add_u64 v[228:229], s[14:15], 0, v[188:189]
	s_mov_b32 m0, s62
	s_nop 0
	global_load_lds_dwordx4 v[228:229], off
	s_waitcnt vmcnt(8)
	s_waitcnt lgkmcnt(0)
	s_barrier
	s_waitcnt lgkmcnt(0)
	v_mfma_f32_16x16x32_bf16 v[144:147], v[52:55], v[164:167], v[144:147]
	v_mfma_f32_16x16x32_bf16 v[140:143], v[68:71], v[164:167], v[140:143]
	v_mfma_f32_16x16x32_bf16 v[128:131], v[52:55], v[172:175], v[128:131]
	v_mfma_f32_16x16x32_bf16 v[124:127], v[68:71], v[172:175], v[124:127]
	v_mfma_f32_16x16x32_bf16 v[112:115], v[52:55], v[196:199], v[112:115]
	v_mfma_f32_16x16x32_bf16 v[108:111], v[68:71], v[196:199], v[108:111]
	v_mfma_f32_16x16x32_bf16 v[96:99], v[52:55], v[204:207], v[96:99]
	v_mfma_f32_16x16x32_bf16 v[92:95], v[68:71], v[204:207], v[92:95]
	v_mfma_f32_16x16x32_bf16 v[144:147], v[56:59], v[168:171], v[144:147]
	v_mfma_f32_16x16x32_bf16 v[140:143], v[72:75], v[168:171], v[140:143]
	v_mfma_f32_16x16x32_bf16 v[128:131], v[56:59], v[176:179], v[128:131]
	v_mfma_f32_16x16x32_bf16 v[124:127], v[72:75], v[176:179], v[124:127]
	v_mfma_f32_16x16x32_bf16 v[112:115], v[56:59], v[200:203], v[112:115]
	v_mfma_f32_16x16x32_bf16 v[108:111], v[72:75], v[200:203], v[108:111]
	v_mfma_f32_16x16x32_bf16 v[96:99], v[56:59], v[208:211], v[96:99]
	v_mfma_f32_16x16x32_bf16 v[92:95], v[72:75], v[208:211], v[92:95]
	v_mfma_f32_16x16x32_bf16 v[136:139], v[148:151], v[164:167], v[136:139]
	v_mfma_f32_16x16x32_bf16 v[132:135], v[156:159], v[164:167], v[132:135]
	v_mfma_f32_16x16x32_bf16 v[120:123], v[148:151], v[172:175], v[120:123]
	v_mfma_f32_16x16x32_bf16 v[116:119], v[156:159], v[172:175], v[116:119]
	v_mfma_f32_16x16x32_bf16 v[104:107], v[148:151], v[196:199], v[104:107]
	v_mfma_f32_16x16x32_bf16 v[100:103], v[156:159], v[196:199], v[100:103]
	v_mfma_f32_16x16x32_bf16 v[88:91], v[148:151], v[204:207], v[88:91]
	v_mfma_f32_16x16x32_bf16 v[84:87], v[156:159], v[204:207], v[84:87]
	v_mfma_f32_16x16x32_bf16 v[136:139], v[152:155], v[168:171], v[136:139]
	v_mfma_f32_16x16x32_bf16 v[132:135], v[160:163], v[168:171], v[132:135]
	v_mfma_f32_16x16x32_bf16 v[120:123], v[152:155], v[176:179], v[120:123]
	v_mfma_f32_16x16x32_bf16 v[116:119], v[160:163], v[176:179], v[116:119]
	v_mfma_f32_16x16x32_bf16 v[104:107], v[152:155], v[200:203], v[104:107]
	v_mfma_f32_16x16x32_bf16 v[100:103], v[160:163], v[200:203], v[100:103]
	v_mfma_f32_16x16x32_bf16 v[88:91], v[152:155], v[208:211], v[88:91]
	v_mfma_f32_16x16x32_bf16 v[84:87], v[160:163], v[208:211], v[84:87]
	s_barrier
	s_mov_b32 m0, s64
	v_lshl_add_u64 v[212:213], v[212:213], 0, s[96:97]
	ds_read_b128 v[164:167], v216 offset:49152
	ds_read_b128 v[168:171], v216 offset:50176
	ds_read_b128 v[172:175], v216 offset:51200
	ds_read_b128 v[176:179], v216 offset:52224
	ds_read_b128 v[196:199], v216 offset:53248
	ds_read_b128 v[200:203], v216 offset:54272
	ds_read_b128 v[204:207], v216 offset:55296
	ds_read_b128 v[208:211], v216 offset:56320
	global_load_lds_dwordx4 v[212:213], off
	v_lshl_add_u64 v[212:213], v[218:219], 0, s[96:97]
	s_mov_b32 m0, s65
	s_nop 0
	global_load_lds_dwordx4 v[212:213], off
	v_lshl_add_u64 v[212:213], v[220:221], 0, s[96:97]
	s_mov_b32 m0, s69
	s_nop 0
	global_load_lds_dwordx4 v[212:213], off
	v_lshl_add_u64 v[212:213], v[222:223], 0, s[96:97]
	s_mov_b32 m0, s70
	s_nop 0
	global_load_lds_dwordx4 v[212:213], off
	v_lshl_add_u64 v[212:213], v[224:225], 0, s[96:97]
	s_mov_b32 m0, s66
	s_nop 0
	global_load_lds_dwordx4 v[212:213], off
	v_lshl_add_u64 v[212:213], v[226:227], 0, s[96:97]
	s_mov_b32 m0, s67
	s_nop 0
	global_load_lds_dwordx4 v[212:213], off
	s_waitcnt vmcnt(8)
	s_waitcnt lgkmcnt(0)
	s_barrier
	s_waitcnt lgkmcnt(0)
	v_mfma_f32_16x16x32_bf16 v[80:83], v[52:55], v[164:167], v[80:83]
	v_mfma_f32_16x16x32_bf16 v[76:79], v[68:71], v[164:167], v[76:79]
	v_mfma_f32_16x16x32_bf16 v[64:67], v[52:55], v[172:175], v[64:67]
	v_mfma_f32_16x16x32_bf16 v[60:63], v[68:71], v[172:175], v[60:63]
	v_mfma_f32_16x16x32_bf16 v[32:35], v[52:55], v[196:199], v[32:35]
	v_mfma_f32_16x16x32_bf16 v[28:31], v[68:71], v[196:199], v[28:31]
	v_mfma_f32_16x16x32_bf16 v[16:19], v[52:55], v[204:207], v[16:19]
	v_mfma_f32_16x16x32_bf16 v[12:15], v[68:71], v[204:207], v[12:15]
	v_mfma_f32_16x16x32_bf16 v[80:83], v[56:59], v[168:171], v[80:83]
	v_mfma_f32_16x16x32_bf16 v[76:79], v[72:75], v[168:171], v[76:79]
	v_mfma_f32_16x16x32_bf16 v[64:67], v[56:59], v[176:179], v[64:67]
	v_mfma_f32_16x16x32_bf16 v[60:63], v[72:75], v[176:179], v[60:63]
	v_mfma_f32_16x16x32_bf16 v[32:35], v[56:59], v[200:203], v[32:35]
	v_mfma_f32_16x16x32_bf16 v[28:31], v[72:75], v[200:203], v[28:31]
	v_mfma_f32_16x16x32_bf16 v[16:19], v[56:59], v[208:211], v[16:19]
	v_mfma_f32_16x16x32_bf16 v[12:15], v[72:75], v[208:211], v[12:15]
	v_mfma_f32_16x16x32_bf16 v[36:39], v[148:151], v[164:167], v[36:39]
	v_mfma_f32_16x16x32_bf16 v[72:75], v[152:155], v[168:171], v[36:39]
	v_mfma_f32_16x16x32_bf16 v[36:39], v[156:159], v[164:167], v[40:43]
	v_mfma_f32_16x16x32_bf16 v[68:71], v[160:163], v[168:171], v[36:39]
	v_mfma_f32_16x16x32_bf16 v[36:39], v[148:151], v[172:175], v[48:51]
	v_mfma_f32_16x16x32_bf16 v[52:55], v[152:155], v[176:179], v[36:39]
	v_mfma_f32_16x16x32_bf16 v[36:39], v[156:159], v[172:175], v[44:47]
	v_mfma_f32_16x16x32_bf16 v[24:27], v[148:151], v[196:199], v[24:27]
	v_mfma_f32_16x16x32_bf16 v[20:23], v[156:159], v[196:199], v[20:23]
	v_mfma_f32_16x16x32_bf16 v[8:11], v[148:151], v[204:207], v[8:11]
	v_mfma_f32_16x16x32_bf16 v[4:7], v[156:159], v[204:207], v[4:7]
	v_mfma_f32_16x16x32_bf16 v[44:47], v[160:163], v[176:179], v[36:39]
	v_mfma_f32_16x16x32_bf16 v[24:27], v[152:155], v[200:203], v[24:27]
	v_mfma_f32_16x16x32_bf16 v[20:23], v[160:163], v[200:203], v[20:23]
	v_mfma_f32_16x16x32_bf16 v[8:11], v[152:155], v[208:211], v[8:11]
	v_mfma_f32_16x16x32_bf16 v[4:7], v[160:163], v[208:211], v[4:7]
	s_barrier
	s_add_u32 s12, s12, 0x100
	s_addc_u32 s13, s13, 0
	s_add_u32 s2, s2, 0x100
	s_addc_u32 s3, s3, 0
	s_cmp_ge_u32 s46, s73
	s_mov_b32 s14, s46
; #define PG8_STAGE(bufoff, gbase, voff) do { _Pragma("unroll") for (int _i = 0; _i < 2; ++_i) \
;         __builtin_amdgcn_global_load_lds((const unsigned*)((const char*)(gbase) + (voff)[_i]), (PG8_LAS unsigned*)(lds + (bufoff) + ldsw + _i * 8192), 16, 0, 0); } while (0)
; #define PG8_LDA(dst, b, h) do { _Pragma("unroll") for (int m = 0; m < 4; ++m) _Pragma("unroll") for (int k = 0; k < 2; ++k) dst[m][k] = *(const PG8_LAS bf16x8*)(lds + PG8_SA(b, h) + aoff + m * 2048 + k * 1024); } while (0)
; #define PG8_LDB(dst, b, h) do { _Pragma("unroll") for (int n = 0; n < 2; ++n) _Pragma("unroll") for (int k = 0; k < 2; ++k) dst[n][k] = *(const PG8_LAS bf16x8*)(lds + PG8_SB(b, h) + boff + n * 2048 + k * 1024); } while (0)
; #define PG8_MMA(ai, bj, At, Bt) do { __builtin_amdgcn_s_setprio(1); _Pragma("unroll") for (int m = 0; m < 4; ++m) _Pragma("unroll") for (int n = 0; n < 2; ++n) _Pragma("unroll") for (int k = 0; k < 2; ++k) \
;         acc[ai][bj][m][n] = __builtin_amdgcn_mfma_f32_16x16x32_bf16(Bt[n][k], At[m][k], acc[ai][bj][m][n], 0, 0, 0); __builtin_amdgcn_s_setprio(0); } while (0)
; #define PG8_WAIT_V(n) asm volatile("s_waitcnt vmcnt(" #n ")" ::: "memory")
; #define PG8_WAIT_L(n) asm volatile("s_waitcnt lgkmcnt(" #n ")" ::: "memory")
; template <class Epi, class Sched, bool ALIGN_EPI = false, bool SP2 = false>
; __device__ __forceinline__ void gemm_phase(PG8_LAS unsigned char* lds, const Gemm g, const Sched& S, const Epi& E, const int tid_) {
;     ...
;             const bool last = (t == nt - 2);
;             const char* a1 = cA + (size_t)(t + 1) * kstep;
;             const char* a2 = last ? nA : cA + (size_t)(t + 2) * kstep; const char* b2 = last ? nB : cB + (size_t)(t + 2) * kstep;
;             const char* a3 = a2 + kstep; const char* b3 = b2 + kstep;
;             if (last && has_next) S.a_ready(nxt);
;             if constexpr (SP2) {
;             PG8_LDB(B0, 0, 0); PG8_LDB(B1, 0, 1); PG8_SCHED; PG8_LDA(At, 0, 0); PG8_STAGE(PG8_SA(1, 1), a1 + hstep, voffA);
;             PG8_WAIT_V(8); PG8_WAIT_L(0); PG8_BAR; PG8_MMA(0, 0, At, B0); PG8_MMA(0, 1, At, B1); PG8_BAR; PG8_SCHED;
;             PG8_LDA(At, 0, 1); PG8_STAGE(PG8_SB(0, 0), b2, voffB); PG8_STAGE(PG8_SB(0, 1), b2 + hstepB, voffB); PG8_STAGE(PG8_SA(0, 0), a2, voffA);
;             PG8_WAIT_V(8); PG8_WAIT_L(0); PG8_BAR; PG8_MMA(1, 0, At, B0); PG8_MMA(1, 1, At, B1); PG8_BAR; PG8_SCHED;
.LBB0_528:
	v_add_u32_e32 v56, s53, v214
	v_add_u32_e32 v160, s56, v214
	ds_read_b128 v[36:39], v56
	ds_read_b128 v[40:43], v56 offset:1024
	ds_read_b128 v[48:51], v56 offset:2048
	ds_read_b128 v[56:59], v56 offset:3072
	ds_read_b128 v[148:151], v160
	ds_read_b128 v[152:155], v160 offset:1024
	ds_read_b128 v[156:159], v160 offset:2048
	ds_read_b128 v[160:163], v160 offset:3072
	s_add_i32 s46, s14, 2
	s_add_u32 s47, s12, 0x80
	s_addc_u32 s15, s13, 0
	s_cmp_eq_u32 s74, s14
	s_cselect_b32 s14, s42, s47
	s_cselect_b32 s15, s43, s15
	s_cselect_b32 s49, s45, s3
	s_cselect_b32 s48, s44, s2
	v_lshl_add_u64 v[212:213], s[12:13], 0, v[192:193]
	s_add_i32 m0, s59, 0xc000
	ds_read_b128 v[164:167], v216
	ds_read_b128 v[168:171], v216 offset:1024
	ds_read_b128 v[172:175], v216 offset:2048
	ds_read_b128 v[176:179], v216 offset:3072
	ds_read_b128 v[196:199], v216 offset:4096
	ds_read_b128 v[200:203], v216 offset:5120
	ds_read_b128 v[204:207], v216 offset:6144
	ds_read_b128 v[208:211], v216 offset:7168
	global_load_lds_dwordx4 v[212:213], off
	v_lshl_add_u64 v[212:213], s[12:13], 0, v[194:195]
	s_add_i32 m0, s59, 0xe000
	s_nop 0
	global_load_lds_dwordx4 v[212:213], off
	s_waitcnt vmcnt(8)
	s_waitcnt lgkmcnt(0)
	s_barrier
	s_waitcnt lgkmcnt(0)
	v_mfma_f32_16x16x32_bf16 v[144:147], v[36:39], v[164:167], v[144:147]
	v_mfma_f32_16x16x32_bf16 v[140:143], v[48:51], v[164:167], v[140:143]
	v_mfma_f32_16x16x32_bf16 v[128:131], v[36:39], v[172:175], v[128:131]
	v_mfma_f32_16x16x32_bf16 v[124:127], v[48:51], v[172:175], v[124:127]
	v_mfma_f32_16x16x32_bf16 v[112:115], v[36:39], v[196:199], v[112:115]
	v_mfma_f32_16x16x32_bf16 v[108:111], v[48:51], v[196:199], v[108:111]
	v_mfma_f32_16x16x32_bf16 v[96:99], v[36:39], v[204:207], v[96:99]
	v_mfma_f32_16x16x32_bf16 v[92:95], v[48:51], v[204:207], v[92:95]
	v_mfma_f32_16x16x32_bf16 v[144:147], v[40:43], v[168:171], v[144:147]
	v_mfma_f32_16x16x32_bf16 v[140:143], v[56:59], v[168:171], v[140:143]
	v_mfma_f32_16x16x32_bf16 v[128:131], v[40:43], v[176:179], v[128:131]
	v_mfma_f32_16x16x32_bf16 v[124:127], v[56:59], v[176:179], v[124:127]
	v_mfma_f32_16x16x32_bf16 v[112:115], v[40:43], v[200:203], v[112:115]
	v_mfma_f32_16x16x32_bf16 v[108:111], v[56:59], v[200:203], v[108:111]
	v_mfma_f32_16x16x32_bf16 v[96:99], v[40:43], v[208:211], v[96:99]
	v_mfma_f32_16x16x32_bf16 v[92:95], v[56:59], v[208:211], v[92:95]
	v_mfma_f32_16x16x32_bf16 v[136:139], v[148:151], v[164:167], v[136:139]
	v_mfma_f32_16x16x32_bf16 v[132:135], v[156:159], v[164:167], v[132:135]
	v_mfma_f32_16x16x32_bf16 v[120:123], v[148:151], v[172:175], v[120:123]
	v_mfma_f32_16x16x32_bf16 v[116:119], v[156:159], v[172:175], v[116:119]
	v_mfma_f32_16x16x32_bf16 v[104:107], v[148:151], v[196:199], v[104:107]
	v_mfma_f32_16x16x32_bf16 v[100:103], v[156:159], v[196:199], v[100:103]
	v_mfma_f32_16x16x32_bf16 v[88:91], v[148:151], v[204:207], v[88:91]
	v_mfma_f32_16x16x32_bf16 v[84:87], v[156:159], v[204:207], v[84:87]
	v_mfma_f32_16x16x32_bf16 v[136:139], v[152:155], v[168:171], v[136:139]
	v_mfma_f32_16x16x32_bf16 v[132:135], v[160:163], v[168:171], v[132:135]
	v_mfma_f32_16x16x32_bf16 v[120:123], v[152:155], v[176:179], v[120:123]
	v_mfma_f32_16x16x32_bf16 v[116:119], v[160:163], v[176:179], v[116:119]
	v_mfma_f32_16x16x32_bf16 v[104:107], v[152:155], v[200:203], v[104:107]
	v_mfma_f32_16x16x32_bf16 v[100:103], v[160:163], v[200:203], v[100:103]
	v_mfma_f32_16x16x32_bf16 v[88:91], v[152:155], v[208:211], v[88:91]
	v_mfma_f32_16x16x32_bf16 v[84:87], v[160:163], v[208:211], v[84:87]
	s_barrier
	s_mov_b32 m0, s54
	v_lshl_add_u64 v[212:213], s[48:49], 0, v[2:3]
	v_lshl_add_u64 v[218:219], s[48:49], 0, v[190:191]
	s_add_u32 s48, s48, s52
	ds_read_b128 v[164:167], v216 offset:16384
	ds_read_b128 v[168:171], v216 offset:17408
	ds_read_b128 v[172:175], v216 offset:18432
	ds_read_b128 v[176:179], v216 offset:19456
	ds_read_b128 v[196:199], v216 offset:20480
	ds_read_b128 v[200:203], v216 offset:21504
	ds_read_b128 v[204:207], v216 offset:22528
	ds_read_b128 v[208:211], v216 offset:23552
	global_load_lds_dwordx4 v[212:213], off
	s_mov_b32 m0, s55
	s_addc_u32 s49, s49, 0
	global_load_lds_dwordx4 v[218:219], off
	v_lshl_add_u64 v[220:221], s[48:49], 0, v[2:3]
	s_mov_b32 m0, s57
	v_lshl_add_u64 v[222:223], s[48:49], 0, v[190:191]
	global_load_lds_dwordx4 v[220:221], off
	s_mov_b32 m0, s58
	v_lshl_add_u64 v[224:225], s[14:15], 0, v[0:1]
	global_load_lds_dwordx4 v[222:223], off
	s_mov_b32 m0, s59
	v_lshl_add_u64 v[226:227], s[14:15], 0, v[188:189]
	global_load_lds_dwordx4 v[224:225], off
	s_mov_b32 m0, s60
	s_nop 0
	global_load_lds_dwordx4 v[226:227], off
	s_waitcnt vmcnt(8)
	s_waitcnt lgkmcnt(0)
	s_barrier
; #define PG8_STAGE(bufoff, gbase, voff) do { _Pragma("unroll") for (int _i = 0; _i < 2; ++_i) \
;         __builtin_amdgcn_global_load_lds((const unsigned*)((const char*)(gbase) + (voff)[_i]), (PG8_LAS unsigned*)(lds + (bufoff) + ldsw + _i * 8192), 16, 0, 0); } while (0)
; #define PG8_LDA(dst, b, h) do { _Pragma("unroll") for (int m = 0; m < 4; ++m) _Pragma("unroll") for (int k = 0; k < 2; ++k) dst[m][k] = *(const PG8_LAS bf16x8*)(lds + PG8_SA(b, h) + aoff + m * 2048 + k * 1024); } while (0)
; #define PG8_LDB(dst, b, h) do { _Pragma("unroll") for (int n = 0; n < 2; ++n) _Pragma("unroll") for (int k = 0; k < 2; ++k) dst[n][k] = *(const PG8_LAS bf16x8*)(lds + PG8_SB(b, h) + boff + n * 2048 + k * 1024); } while (0)
; #define PG8_MMA(ai, bj, At, Bt) do { __builtin_amdgcn_s_setprio(1); _Pragma("unroll") for (int m = 0; m < 4; ++m) _Pragma("unroll") for (int n = 0; n < 2; ++n) _Pragma("unroll") for (int k = 0; k < 2; ++k) \
;         acc[ai][bj][m][n] = __builtin_amdgcn_mfma_f32_16x16x32_bf16(Bt[n][k], At[m][k], acc[ai][bj][m][n], 0, 0, 0); __builtin_amdgcn_s_setprio(0); } while (0)
; #define PG8_WAIT_V(n) asm volatile("s_waitcnt vmcnt(" #n ")" ::: "memory")
; #define PG8_WAIT_L(n) asm volatile("s_waitcnt lgkmcnt(" #n ")" ::: "memory")
; #define PG8_BAR __builtin_amdgcn_s_barrier()
; #define PG8_SCHED __builtin_amdgcn_sched_barrier(0)
; template <class Epi, class Sched, bool ALIGN_EPI = false, bool SP2 = false>
; __device__ __forceinline__ void gemm_phase(PG8_LAS unsigned char* lds, const Gemm g, const Sched& S, const Epi& E, const int tid_) {
;     ...
;             PG8_WAIT_V(8); PG8_WAIT_L(0); PG8_BAR; PG8_MMA(1, 0, At, B0); PG8_MMA(1, 1, At, B1); PG8_BAR; PG8_SCHED;
;             PG8_LDB(B0, 1, 0); PG8_LDB(B1, 1, 1); PG8_SCHED; PG8_LDA(At, 1, 0); PG8_STAGE(PG8_SA(0, 1), a2 + hstep, voffA);
;             PG8_WAIT_V(8); PG8_WAIT_L(0); PG8_BAR; PG8_MMA(0, 0, At, B0); PG8_MMA(0, 1, At, B1); PG8_BAR; PG8_SCHED;
	s_waitcnt lgkmcnt(0)
	v_mfma_f32_16x16x32_bf16 v[80:83], v[36:39], v[164:167], v[80:83]
	v_mfma_f32_16x16x32_bf16 v[76:79], v[48:51], v[164:167], v[76:79]
	v_mfma_f32_16x16x32_bf16 v[64:67], v[36:39], v[172:175], v[64:67]
	v_mfma_f32_16x16x32_bf16 v[60:63], v[48:51], v[172:175], v[60:63]
	v_mfma_f32_16x16x32_bf16 v[32:35], v[36:39], v[196:199], v[32:35]
	v_mfma_f32_16x16x32_bf16 v[28:31], v[48:51], v[196:199], v[28:31]
	v_mfma_f32_16x16x32_bf16 v[16:19], v[36:39], v[204:207], v[16:19]
	v_mfma_f32_16x16x32_bf16 v[12:15], v[48:51], v[204:207], v[12:15]
	v_mfma_f32_16x16x32_bf16 v[80:83], v[40:43], v[168:171], v[80:83]
	v_mfma_f32_16x16x32_bf16 v[76:79], v[56:59], v[168:171], v[76:79]
	v_mfma_f32_16x16x32_bf16 v[64:67], v[40:43], v[176:179], v[64:67]
	v_mfma_f32_16x16x32_bf16 v[60:63], v[56:59], v[176:179], v[60:63]
	v_mfma_f32_16x16x32_bf16 v[32:35], v[40:43], v[200:203], v[32:35]
	v_mfma_f32_16x16x32_bf16 v[28:31], v[56:59], v[200:203], v[28:31]
	v_mfma_f32_16x16x32_bf16 v[16:19], v[40:43], v[208:211], v[16:19]
	v_mfma_f32_16x16x32_bf16 v[12:15], v[56:59], v[208:211], v[12:15]
	v_mfma_f32_16x16x32_bf16 v[44:47], v[156:159], v[172:175], v[44:47]
	v_mfma_f32_16x16x32_bf16 v[24:27], v[148:151], v[196:199], v[24:27]
	v_mfma_f32_16x16x32_bf16 v[20:23], v[156:159], v[196:199], v[20:23]
	v_mfma_f32_16x16x32_bf16 v[8:11], v[148:151], v[204:207], v[8:11]
	v_mfma_f32_16x16x32_bf16 v[4:7], v[156:159], v[204:207], v[4:7]
	v_mfma_f32_16x16x32_bf16 v[36:39], v[148:151], v[164:167], v[72:75]
	v_mfma_f32_16x16x32_bf16 v[40:43], v[156:159], v[164:167], v[68:71]
	v_mfma_f32_16x16x32_bf16 v[48:51], v[148:151], v[172:175], v[52:55]
	v_mfma_f32_16x16x32_bf16 v[44:47], v[160:163], v[176:179], v[44:47]
	v_mfma_f32_16x16x32_bf16 v[24:27], v[152:155], v[200:203], v[24:27]
	v_mfma_f32_16x16x32_bf16 v[20:23], v[160:163], v[200:203], v[20:23]
	v_mfma_f32_16x16x32_bf16 v[8:11], v[152:155], v[208:211], v[8:11]
	v_mfma_f32_16x16x32_bf16 v[4:7], v[160:163], v[208:211], v[4:7]
	v_mfma_f32_16x16x32_bf16 v[36:39], v[152:155], v[168:171], v[36:39]
	v_mfma_f32_16x16x32_bf16 v[40:43], v[160:163], v[168:171], v[40:43]
	v_mfma_f32_16x16x32_bf16 v[48:51], v[152:155], v[176:179], v[48:51]
	s_barrier
	v_add_u32_e32 v72, s63, v214
	v_add_u32_e32 v160, s68, v214
	ds_read_b128 v[52:55], v72
	ds_read_b128 v[56:59], v72 offset:1024
	ds_read_b128 v[68:71], v72 offset:2048
	ds_read_b128 v[72:75], v72 offset:3072
	ds_read_b128 v[148:151], v160
	ds_read_b128 v[152:155], v160 offset:1024
	ds_read_b128 v[156:159], v160 offset:2048
	ds_read_b128 v[160:163], v160 offset:3072
	s_add_u32 s14, s14, s24
	s_addc_u32 s15, s15, 0
	s_mov_b32 m0, s61
	v_lshl_add_u64 v[228:229], s[14:15], 0, v[0:1]
	ds_read_b128 v[164:167], v216 offset:32768
	ds_read_b128 v[168:171], v216 offset:33792
	ds_read_b128 v[172:175], v216 offset:34816
	ds_read_b128 v[176:179], v216 offset:35840
	ds_read_b128 v[196:199], v216 offset:36864
	ds_read_b128 v[200:203], v216 offset:37888
	ds_read_b128 v[204:207], v216 offset:38912
	ds_read_b128 v[208:211], v216 offset:39936
	global_load_lds_dwordx4 v[228:229], off
	v_lshl_add_u64 v[228:229], s[14:15], 0, v[188:189]
	s_mov_b32 m0, s62
	s_nop 0
	global_load_lds_dwordx4 v[228:229], off
	s_waitcnt vmcnt(8)
	s_waitcnt lgkmcnt(0)
	s_barrier
	s_waitcnt lgkmcnt(0)
	v_mfma_f32_16x16x32_bf16 v[144:147], v[52:55], v[164:167], v[144:147]
	v_mfma_f32_16x16x32_bf16 v[140:143], v[68:71], v[164:167], v[140:143]
	v_mfma_f32_16x16x32_bf16 v[128:131], v[52:55], v[172:175], v[128:131]
	v_mfma_f32_16x16x32_bf16 v[124:127], v[68:71], v[172:175], v[124:127]
	v_mfma_f32_16x16x32_bf16 v[112:115], v[52:55], v[196:199], v[112:115]
	v_mfma_f32_16x16x32_bf16 v[108:111], v[68:71], v[196:199], v[108:111]
	v_mfma_f32_16x16x32_bf16 v[96:99], v[52:55], v[204:207], v[96:99]
	v_mfma_f32_16x16x32_bf16 v[92:95], v[68:71], v[204:207], v[92:95]
	v_mfma_f32_16x16x32_bf16 v[144:147], v[56:59], v[168:171], v[144:147]
	v_mfma_f32_16x16x32_bf16 v[140:143], v[72:75], v[168:171], v[140:143]
	v_mfma_f32_16x16x32_bf16 v[128:131], v[56:59], v[176:179], v[128:131]
	v_mfma_f32_16x16x32_bf16 v[124:127], v[72:75], v[176:179], v[124:127]
	v_mfma_f32_16x16x32_bf16 v[112:115], v[56:59], v[200:203], v[112:115]
	v_mfma_f32_16x16x32_bf16 v[108:111], v[72:75], v[200:203], v[108:111]
	v_mfma_f32_16x16x32_bf16 v[96:99], v[56:59], v[208:211], v[96:99]
	v_mfma_f32_16x16x32_bf16 v[92:95], v[72:75], v[208:211], v[92:95]
	v_mfma_f32_16x16x32_bf16 v[136:139], v[148:151], v[164:167], v[136:139]
	v_mfma_f32_16x16x32_bf16 v[132:135], v[156:159], v[164:167], v[132:135]
	v_mfma_f32_16x16x32_bf16 v[120:123], v[148:151], v[172:175], v[120:123]
	v_mfma_f32_16x16x32_bf16 v[116:119], v[156:159], v[172:175], v[116:119]
	v_mfma_f32_16x16x32_bf16 v[104:107], v[148:151], v[196:199], v[104:107]
	v_mfma_f32_16x16x32_bf16 v[100:103], v[156:159], v[196:199], v[100:103]
	v_mfma_f32_16x16x32_bf16 v[88:91], v[148:151], v[204:207], v[88:91]
	v_mfma_f32_16x16x32_bf16 v[84:87], v[156:159], v[204:207], v[84:87]
	v_mfma_f32_16x16x32_bf16 v[136:139], v[152:155], v[168:171], v[136:139]
	v_mfma_f32_16x16x32_bf16 v[132:135], v[160:163], v[168:171], v[132:135]
	v_mfma_f32_16x16x32_bf16 v[120:123], v[152:155], v[176:179], v[120:123]
	v_mfma_f32_16x16x32_bf16 v[116:119], v[160:163], v[176:179], v[116:119]
	v_mfma_f32_16x16x32_bf16 v[104:107], v[152:155], v[200:203], v[104:107]
	v_mfma_f32_16x16x32_bf16 v[100:103], v[160:163], v[200:203], v[100:103]
	v_mfma_f32_16x16x32_bf16 v[88:91], v[152:155], v[208:211], v[88:91]
	v_mfma_f32_16x16x32_bf16 v[84:87], v[160:163], v[208:211], v[84:87]
	s_barrier
; #define PG8_STAGE(bufoff, gbase, voff) do { _Pragma("unroll") for (int _i = 0; _i < 2; ++_i) \
;         __builtin_amdgcn_global_load_lds((const unsigned*)((const char*)(gbase) + (voff)[_i]), (PG8_LAS unsigned*)(lds + (bufoff) + ldsw + _i * 8192), 16, 0, 0); } while (0)
; #define PG8_LDA(dst, b, h) do { _Pragma("unroll") for (int m = 0; m < 4; ++m) _Pragma("unroll") for (int k = 0; k < 2; ++k) dst[m][k] = *(const PG8_LAS bf16x8*)(lds + PG8_SA(b, h) + aoff + m * 2048 + k * 1024); } while (0)
; #define PG8_MMA(ai, bj, At, Bt) do { __builtin_amdgcn_s_setprio(1); _Pragma("unroll") for (int m = 0; m < 4; ++m) _Pragma("unroll") for (int n = 0; n < 2; ++n) _Pragma("unroll") for (int k = 0; k < 2; ++k) \
;         acc[ai][bj][m][n] = __builtin_amdgcn_mfma_f32_16x16x32_bf16(Bt[n][k], At[m][k], acc[ai][bj][m][n], 0, 0, 0); __builtin_amdgcn_s_setprio(0); } while (0)
; #define PG8_WAIT_V(n) asm volatile("s_waitcnt vmcnt(" #n ")" ::: "memory")
; #define PG8_WAIT_L(n) asm volatile("s_waitcnt lgkmcnt(" #n ")" ::: "memory")
; #define PG8_BAR __builtin_amdgcn_s_barrier()
; #define PG8_SCHED __builtin_amdgcn_sched_barrier(0)
;     __device__ __forceinline__ void operator()(const f32x4 (&acc)[2][2][4][2], const Unit& u, int wr, int wc, int fr, int fq) const {
;         const int row0 = u.pm * BM + wr * 64 + fr; const int col0 = u.pn * BM + wc * 64 + 8 * fq;
;         f32x4 bv[2][2];
; #pragma unroll
;         for (int bj = 0; bj < 2; ++bj)
; #pragma unroll
;             for (int n = 0; n < 2; ++n) bv[bj][n] = bias ? *(const f32x4*)(bias + col0 + bj * 32 + 4 * n) : (f32x4){0.f, 0.f, 0.f, 0.f};
; template <class Epi, class Sched, bool ALIGN_EPI = false, bool SP2 = false>
; __device__ __forceinline__ void gemm_phase(PG8_LAS unsigned char* lds, const Gemm g, const Sched& S, const Epi& E, const int tid_) {
;     ...
;             PG8_LDA(At, 1, 1); PG8_STAGE(PG8_SB(1, 0), b3, voffB); PG8_STAGE(PG8_SB(1, 1), b3 + hstepB, voffB); PG8_STAGE(PG8_SA(1, 0), a3, voffA);
;             PG8_WAIT_V(8); PG8_WAIT_L(0); PG8_BAR; PG8_MMA(1, 0, At, B0); PG8_MMA(1, 1, At, B1); PG8_BAR; PG8_SCHED;
	s_mov_b32 m0, s64
	v_lshl_add_u64 v[212:213], v[212:213], 0, s[96:97]
	ds_read_b128 v[164:167], v216 offset:49152
	ds_read_b128 v[168:171], v216 offset:50176
	ds_read_b128 v[172:175], v216 offset:51200
	ds_read_b128 v[176:179], v216 offset:52224
	ds_read_b128 v[196:199], v216 offset:53248
	ds_read_b128 v[200:203], v216 offset:54272
	ds_read_b128 v[204:207], v216 offset:55296
	ds_read_b128 v[208:211], v216 offset:56320
	global_load_lds_dwordx4 v[212:213], off
	v_lshl_add_u64 v[212:213], v[218:219], 0, s[96:97]
	s_mov_b32 m0, s65
	s_nop 0
	global_load_lds_dwordx4 v[212:213], off
	v_lshl_add_u64 v[212:213], v[220:221], 0, s[96:97]
	s_mov_b32 m0, s69
	s_nop 0
	global_load_lds_dwordx4 v[212:213], off
	v_lshl_add_u64 v[212:213], v[222:223], 0, s[96:97]
	s_mov_b32 m0, s70
	s_nop 0
	global_load_lds_dwordx4 v[212:213], off
	v_lshl_add_u64 v[212:213], v[224:225], 0, s[96:97]
	s_mov_b32 m0, s66
	s_nop 0
	global_load_lds_dwordx4 v[212:213], off
	v_lshl_add_u64 v[212:213], v[226:227], 0, s[96:97]
	s_mov_b32 m0, s67
	s_nop 0
	global_load_lds_dwordx4 v[212:213], off
	s_waitcnt vmcnt(8)
	s_waitcnt lgkmcnt(0)
	s_barrier
	s_waitcnt lgkmcnt(0)
	v_mfma_f32_16x16x32_bf16 v[80:83], v[52:55], v[164:167], v[80:83]
	v_mfma_f32_16x16x32_bf16 v[76:79], v[68:71], v[164:167], v[76:79]
	v_mfma_f32_16x16x32_bf16 v[64:67], v[52:55], v[172:175], v[64:67]
	v_mfma_f32_16x16x32_bf16 v[60:63], v[68:71], v[172:175], v[60:63]
	v_mfma_f32_16x16x32_bf16 v[32:35], v[52:55], v[196:199], v[32:35]
	v_mfma_f32_16x16x32_bf16 v[28:31], v[68:71], v[196:199], v[28:31]
	v_mfma_f32_16x16x32_bf16 v[16:19], v[52:55], v[204:207], v[16:19]
	v_mfma_f32_16x16x32_bf16 v[12:15], v[68:71], v[204:207], v[12:15]
	v_mfma_f32_16x16x32_bf16 v[80:83], v[56:59], v[168:171], v[80:83]
	v_mfma_f32_16x16x32_bf16 v[76:79], v[72:75], v[168:171], v[76:79]
	v_mfma_f32_16x16x32_bf16 v[64:67], v[56:59], v[176:179], v[64:67]
	v_mfma_f32_16x16x32_bf16 v[60:63], v[72:75], v[176:179], v[60:63]
	v_mfma_f32_16x16x32_bf16 v[32:35], v[56:59], v[200:203], v[32:35]
	v_mfma_f32_16x16x32_bf16 v[28:31], v[72:75], v[200:203], v[28:31]
	v_mfma_f32_16x16x32_bf16 v[16:19], v[56:59], v[208:211], v[16:19]
	v_mfma_f32_16x16x32_bf16 v[12:15], v[72:75], v[208:211], v[12:15]
	v_mfma_f32_16x16x32_bf16 v[36:39], v[148:151], v[164:167], v[36:39]
	v_mfma_f32_16x16x32_bf16 v[72:75], v[152:155], v[168:171], v[36:39]
	v_mfma_f32_16x16x32_bf16 v[36:39], v[156:159], v[164:167], v[40:43]
	v_mfma_f32_16x16x32_bf16 v[68:71], v[160:163], v[168:171], v[36:39]
	v_mfma_f32_16x16x32_bf16 v[36:39], v[148:151], v[172:175], v[48:51]
	v_mfma_f32_16x16x32_bf16 v[52:55], v[152:155], v[176:179], v[36:39]
	v_mfma_f32_16x16x32_bf16 v[36:39], v[156:159], v[172:175], v[44:47]
	v_mfma_f32_16x16x32_bf16 v[24:27], v[148:151], v[196:199], v[24:27]
	v_mfma_f32_16x16x32_bf16 v[20:23], v[156:159], v[196:199], v[20:23]
	v_mfma_f32_16x16x32_bf16 v[8:11], v[148:151], v[204:207], v[8:11]
	v_mfma_f32_16x16x32_bf16 v[4:7], v[156:159], v[204:207], v[4:7]
	v_mfma_f32_16x16x32_bf16 v[44:47], v[160:163], v[176:179], v[36:39]
	v_mfma_f32_16x16x32_bf16 v[24:27], v[152:155], v[200:203], v[24:27]
	v_mfma_f32_16x16x32_bf16 v[20:23], v[160:163], v[200:203], v[20:23]
	v_mfma_f32_16x16x32_bf16 v[8:11], v[152:155], v[208:211], v[8:11]
	v_mfma_f32_16x16x32_bf16 v[4:7], v[160:163], v[208:211], v[4:7]
	s_barrier
	s_add_u32 s12, s12, 0x100
	s_addc_u32 s13, s13, 0
	s_add_u32 s2, s2, 0x100
	s_addc_u32 s3, s3, 0
	s_cmp_ge_u32 s46, s73
	s_mov_b32 s14, s46
	s_cbranch_scc0 .LBB0_528
	s_and_b64 vcc, exec, s[36:37]
	s_cbranch_vccnz .Lepi3_old
	s_and_b64 vcc, exec, s[40:41]
	s_cbranch_vccnz .Lepi3_old
	v_lshl_add_u32 v245, s81, 8, v187
	v_lshl_or_b32 v217, s80, 8, v215
	v_lshlrev_b32_e32 v247, 11, v245
	v_lshl_add_u32 v212, v217, 1, v247
	v_lshlrev_b32_e32 v249, 2, v217
	v_mov_b32_e32 v36, 0
	v_mov_b32_e32 v37, 0
	v_mov_b32_e32 v38, 0
	v_mov_b32_e32 v39, 0
	v_mov_b32_e32 v40, 0
	v_mov_b32_e32 v41, 0
	v_mov_b32_e32 v42, 0
	v_mov_b32_e32 v43, 0
	v_mov_b32_e32 v48, 0
	v_mov_b32_e32 v49, 0
	v_mov_b32_e32 v50, 0
	v_mov_b32_e32 v51, 0
	v_mov_b32_e32 v56, 0
	v_mov_b32_e32 v57, 0
	v_mov_b32_e32 v58, 0
	v_mov_b32_e32 v59, 0
	s_and_b64 vcc, exec, s[34:35]
	s_cbranch_vccz .Lepi3_nobias
	global_load_dwordx4 v[56:59], v249, s[18:19]
	global_load_dwordx4 v[48:51], v249, s[18:19] offset:16
	global_load_dwordx4 v[40:43], v249, s[18:19] offset:128
	global_load_dwordx4 v[36:39], v249, s[18:19] offset:144
